# attention loops (A,B,C,X): raised wave priority from the loop top through the score phase, normal priority over exp/PV
# speedup vs baseline: 1.0154x; 1.0077x over previous
; template <int DH, int KT, int NQT, bool PF, class Ctx>
; __device__ __forceinline__ void attn_item(unsigned char* smem, const Ctx& c) {
;     ...
;   for (int t = 0; t < nt; ++t) {
;     __syncthreads();
;     if constexpr (PF) {
;       static_assert(!PF || NCH == 2 || NCH == 4, "wait lists below are written for two or four chunks per matrix");
;       if constexpr (NCH == 2) asm volatile("s_waitcnt vmcnt(0)" : "+v"(rk[0]), "+v"(rk[NCH - 1]), "+v"(rv[0]), "+v"(rv[NCH - 1]) :: "memory");
;       else asm volatile("s_waitcnt vmcnt(0)" : "+v"(rk[0]), "+v"(rk[1]), "+v"(rk[NCH - 2]), "+v"(rk[NCH - 1]), "+v"(rv[0]), "+v"(rv[1]), "+v"(rv[NCH - 2]), "+v"(rv[NCH - 1]) :: "memory");
; #pragma unroll
;       for (int i = 0; i < NCH; ++i) {
;         const int ci = tid + 256 * i, row = ci / CH, ch = ci % CH;
;         *(u32x4*)(sK + row * LDK + ch * 8) = rk[i]; *(u32x4*)(sV + row * LDK + ch * 8) = rv[i];
;       }
;     } else {
; #pragma unroll
;       for (int i = 0; i < NCH; ++i) {
;         const int ci = tid + 256 * i, row = ci / CH, ch = ci % CH;
;     ...
;           float psum = 0.f;
; #pragma unroll
;           for (int k4 = 0; k4 < NK4; ++k4)
; #pragma unroll
;             for (int j = 0; j < 4; ++j) { const float pv = __builtin_amdgcn_exp2f(s[q][k4][j] - mnew); s[q][k4][j] = pv; psum += pv; }
;           lrow[qt] += psum;
; #pragma unroll
;           for (int kk = 0; kk < NKK; ++kk) {
;             u32x4 w;
;             w.x = cvtpk(s[q][2 * kk][0], s[q][2 * kk][1]); w.y = cvtpk(s[q][2 * kk][2], s[q][2 * kk][3]);
;             w.z = cvtpk(s[q][2 * kk + 1][0], s[q][2 * kk + 1][1]); w.w = cvtpk(s[q][2 * kk + 1][2], s[q][2 * kk + 1][3]);
;             pfa[qt][kk] = __builtin_bit_cast(bf16x8, w);
;           }
;         }
;       }
; #pragma unroll
;       for (int kk = 0; kk < NKK; ++kk) {
;         const bf16_t* vb = sV + (32 * kk + 4 * quad + (l15 >> 2)) * LDK + 4 * (l15 & 3);
; #pragma unroll
;         for (int dt = 0; dt < NDT; ++dt) {
;           const s16x4 lo = tr_read(vb + 16 * dt);
;           const s16x4 hi = tr_read(vb + 16 * LDK + 16 * dt);
;           const bf16x8 vf = (bf16x8){lo[0], lo[1], lo[2], lo[3], hi[0], hi[1], hi[2], hi[3]};
; #pragma unroll
;           for (int qt = 0; qt < NQT; ++qt) o[qt][dt] = __builtin_amdgcn_mfma_f32_16x16x32_bf16(vf, pfa[qt][kk], o[qt][dt], 0, 0, 0);
;         }
;       }
.LBB0_178:
	s_setprio 0
	v_sub_f32_e32 v72, v72, v71
	v_exp_f32_e32 v90, v72
	v_sub_f32_e32 v72, v73, v71
	v_exp_f32_e32 v91, v72
	v_sub_f32_e32 v72, v74, v71
	v_exp_f32_e32 v100, v72
	v_sub_f32_e32 v72, v141, v71
	v_exp_f32_e32 v112, v72
	v_sub_f32_e32 v72, v76, v71
	v_exp_f32_e32 v113, v72
	v_sub_f32_e32 v72, v77, v71
	v_exp_f32_e32 v125, v72
	v_sub_f32_e32 v72, v78, v71
	v_cvt_pk_bf16_f32 v83, v83, v86
	v_cvt_pk_bf16_f32 v86, v134, v135
	v_exp_f32_e32 v134, v72
	v_sub_f32_e32 v72, v79, v71
	v_exp_f32_e32 v135, v72
	v_cvt_pk_bf16_f32 v84, v87, v131
	v_cvt_pk_bf16_f32 v87, v136, v137
	v_add_u32_e32 v136, v115, v116
	v_cvt_pk_bf16_f32 v85, v132, v133
	ds_read_b64_tr_b16 v[78:79], v136 offset:11520
	ds_read_b64_tr_b16 v[76:77], v136 offset:9216
	ds_read_b64_tr_b16 v[108:109], v136 offset:9248
	ds_read_b64_tr_b16 v[126:127], v136 offset:9280
	ds_read_b64_tr_b16 v[130:131], v136 offset:9312
	ds_read_b64_tr_b16 v[110:111], v136 offset:11552
	ds_read_b64_tr_b16 v[128:129], v136 offset:11584
	ds_read_b64_tr_b16 v[132:133], v136 offset:11616
	v_cvt_pk_bf16_f32 v82, v81, v82
	v_cvt_pk_bf16_f32 v89, v140, v80
	v_sub_f32_e32 v80, v75, v71
	v_cvt_pk_bf16_f32 v72, v90, v91
	v_cvt_pk_bf16_f32 v73, v100, v112
	v_cvt_pk_bf16_f32 v74, v113, v125
	v_cvt_pk_bf16_f32 v75, v134, v135
	v_sub_f32_e32 v64, v64, v71
	v_sub_f32_e32 v68, v68, v71
	s_waitcnt lgkmcnt(2)
	v_mfma_f32_16x16x32_bf16 v[12:15], v[108:111], v[82:85], v[12:15]
	v_cvt_pk_bf16_f32 v88, v138, v139
	v_exp_f32_e32 v138, v68
	v_sub_f32_e32 v68, v69, v71
	v_mfma_f32_16x16x32_bf16 v[8:11], v[108:111], v[72:75], v[8:11]
	v_exp_f32_e32 v109, v64
	v_sub_f32_e32 v64, v65, v71
	v_exp_f32_e32 v110, v64
	v_sub_f32_e32 v64, v66, v71
	v_exp_f32_e32 v139, v68
	v_sub_f32_e32 v68, v70, v71
	v_exp_f32_e32 v111, v64
	v_sub_f32_e32 v64, v67, v71
	v_exp_f32_e32 v137, v80
	v_exp_f32_e32 v108, v68
	s_waitcnt lgkmcnt(1)
	v_mfma_f32_16x16x32_bf16 v[16:19], v[126:129], v[82:85], v[16:19]
	v_cvt_pk_bf16_f32 v70, v109, v110
	v_cvt_pk_bf16_f32 v68, v137, v138
	v_cvt_pk_bf16_f32 v69, v139, v108
	v_mfma_f32_16x16x32_bf16 v[4:7], v[126:129], v[72:75], v[4:7]
	v_exp_f32_e32 v126, v64
	ds_read_b64_tr_b16 v[64:65], v136 offset:13824
	ds_read_b64_tr_b16 v[66:67], v136 offset:16128
	v_readlane_b32 s26, v248, 1
	v_mfma_f32_16x16x32_bf16 v[28:31], v[76:79], v[82:85], v[28:31]
	v_cvt_pk_bf16_f32 v71, v111, v126
	v_readlane_b32 s27, v248, 2
	v_mfma_f32_16x16x32_bf16 v[24:27], v[76:79], v[72:75], v[24:27]
	s_waitcnt lgkmcnt(0)
	v_mfma_f32_16x16x32_bf16 v[28:31], v[64:67], v[86:89], v[28:31]
	v_mfma_f32_16x16x32_bf16 v[24:27], v[64:67], v[68:71], v[24:27]
	v_add_f32_e32 v64, 0, v90
	v_add_f32_e32 v64, v91, v64
	v_add_f32_e32 v64, v100, v64
	v_add_f32_e32 v64, v112, v64
	v_add_f32_e32 v64, v113, v64
	v_add_f32_e32 v64, v125, v64
	v_add_f32_e32 v64, v134, v64
	v_add_f32_e32 v64, v135, v64
	v_mfma_f32_16x16x32_bf16 v[20:23], v[130:133], v[82:85], v[20:23]
	v_add_f32_e32 v64, v137, v64
	v_add_f32_e32 v64, v138, v64
	v_add_f32_e32 v64, v139, v64
	v_mfma_f32_16x16x32_bf16 v[0:3], v[130:133], v[72:75], v[0:3]
	ds_read_b64_tr_b16 v[72:73], v136 offset:13856
	ds_read_b64_tr_b16 v[76:77], v136 offset:13888
	ds_read_b64_tr_b16 v[80:81], v136 offset:13920
	ds_read_b64_tr_b16 v[74:75], v136 offset:16160
	ds_read_b64_tr_b16 v[78:79], v136 offset:16192
	ds_read_b64_tr_b16 v[82:83], v136 offset:16224
	v_add_f32_e32 v64, v108, v64
	v_add_f32_e32 v64, v109, v64
	s_waitcnt lgkmcnt(2)
	v_mfma_f32_16x16x32_bf16 v[12:15], v[72:75], v[86:89], v[12:15]
	v_add_f32_e32 v64, v110, v64
	v_add_f32_e32 v64, v111, v64
	v_add_f32_e32 v64, v126, v64
	v_mfma_f32_16x16x32_bf16 v[8:11], v[72:75], v[68:71], v[8:11]
	v_add_f32_e32 v97, v64, v97
	s_waitcnt lgkmcnt(1)
	v_mfma_f32_16x16x32_bf16 v[16:19], v[76:79], v[86:89], v[16:19]
	v_mfma_f32_16x16x32_bf16 v[4:7], v[76:79], v[68:71], v[4:7]
	s_waitcnt lgkmcnt(0)
	v_mfma_f32_16x16x32_bf16 v[20:23], v[80:83], v[86:89], v[20:23]
	v_mfma_f32_16x16x32_bf16 v[0:3], v[80:83], v[68:71], v[0:3]
.LBB0_179:
	s_setprio 0
	s_add_i32 s89, s89, 64
	s_cmpk_eq_i32 s89, 0xc0
	s_cbranch_scc1 .LBB0_185
.LBB0_180:
	s_setprio 1
	s_waitcnt expcnt(7) lgkmcnt(15)
	s_barrier
	s_waitcnt vmcnt(0)
	ds_write_b128 v119, v[48:51]
	ds_write_b128 v119, v[52:55] offset:9216
	ds_write_b128 v120, v[56:59]
	ds_write_b128 v120, v[60:63] offset:9216
	v_add_u32_e32 v48, s89, v124
	v_max_i32_e32 v48, 0, v48
	v_min_i32_e32 v48, s96, v48
	v_add_u32_e32 v56, s89, v123
	v_lshlrev_b32_e32 v48, s93, v48
	v_max_i32_e32 v56, 0, v56
	v_add_u32_e32 v48, s92, v48
	v_min_i32_e32 v56, s96, v56
	v_mad_u64_u32 v[52:53], s[4:5], v48, s97, v[102:103]
	v_lshlrev_b32_e32 v56, s93, v56
	v_lshl_add_u64 v[48:49], v[52:53], 0, s[44:45]
	s_mov_b32 s61, s45
	v_add_u32_e32 v56, s92, v56
	v_lshl_add_u64 v[48:49], v[48:49], 0, v[104:105]
	v_lshl_add_u64 v[52:53], v[52:53], 0, s[60:61]
	v_mad_u64_u32 v[60:61], s[4:5], v56, s97, v[102:103]
	v_lshl_add_u64 v[48:49], v[48:49], 0, s[46:47]
	v_lshl_add_u64 v[52:53], v[52:53], 0, v[104:105]
	v_lshl_add_u64 v[56:57], v[60:61], 0, s[44:45]
	s_waitcnt lgkmcnt(0)
	s_barrier
	global_load_dwordx4 v[48:51], v[48:49], off sc1
	v_lshl_add_u64 v[52:53], v[52:53], 0, s[46:47]
	v_lshl_add_u64 v[56:57], v[56:57], 0, v[106:107]
	v_lshl_add_u64 v[60:61], v[60:61], 0, s[60:61]
	global_load_dwordx4 v[52:55], v[52:53], off sc1
	v_lshl_add_u64 v[56:57], v[56:57], 0, s[46:47]
	v_lshl_add_u64 v[60:61], v[60:61], 0, v[106:107]
	global_load_dwordx4 v[56:59], v[56:57], off sc1
	v_lshl_add_u64 v[60:61], v[60:61], 0, s[46:47]
	global_load_dwordx4 v[60:63], v[60:61], off sc1
	s_cmp_eq_u32 s33, s89
	s_cbranch_scc1 .LBB0_179
; template <int DH, int KT, int NQT, bool PF, class Ctx>
; __device__ __forceinline__ void attn_item(unsigned char* smem, const Ctx& c) {
;     ...
;       for (int g = 0; g < NQT; g += QG) {
;         f32x4 s[QG][NK4];
; #pragma unroll
;         for (int q = 0; q < QG; ++q)
; #pragma unroll
;           for (int k4 = 0; k4 < NK4; ++k4) s[q][k4] = (f32x4){0.f, 0.f, 0.f, 0.f};
; #pragma unroll
;         for (int k4 = 0; k4 < NK4; ++k4)
; #pragma unroll
;           for (int ks = 0; ks < NKS; ++ks) {
;             const bf16x8 kf = *(const bf16x8*)(sK + (16 * k4 + l15) * LDK + ks * 32 + quad * 8);
; #pragma unroll
;             for (int q = 0; q < QG; ++q) s[q][k4] = __builtin_amdgcn_mfma_f32_16x16x32_bf16(kf, qf[g + q][ks], s[q][k4], 0, 0, 0);
;           }
; #pragma unroll
;         for (int q = 0; q < QG; ++q) {
;           const int qt = g + q;
;           float mx = -1e30f;
; #pragma unroll
;           for (int k4 = 0; k4 < NK4; ++k4)
; #pragma unroll
;             for (int j = 0; j < 4; ++j) { const float v = c.score(t, wid, qt * 16 + l15, 16 * k4 + 4 * quad + j, s[q][k4][j]); s[q][k4][j] = v; mx = fmaxf(mx, v); }
	v_cmp_lt_i32_e32 vcc, v215, v216
	v_add_u32_e32 v131, s89, v122
	ds_read_b128 v[72:75], v118 offset:64
	v_cndmask_b32_e32 v64, v214, v215, vcc
	v_lshlrev_b32_e32 v125, 2, v64
	ds_read_b128 v[64:67], v118
	v_subrev_u32_e32 v100, 64, v131
	v_cmp_lt_i32_e64 s[4:5], -1, v100
	v_cmp_gt_i32_e64 s[6:7], s50, v100
	v_cmp_lt_i32_e32 vcc, v217, v216
	s_waitcnt lgkmcnt(0)
	v_mfma_f32_16x16x32_bf16 v[68:71], v[64:67], v[44:47], 0
	ds_read_b128 v[76:79], v118 offset:2368
	v_cndmask_b32_e32 v112, v214, v217, vcc
	v_lshlrev_b32_e32 v126, 2, v112
	s_nop 0
	v_mfma_f32_16x16x32_bf16 v[64:67], v[64:67], v[32:35], 0
	ds_read_b128 v[80:83], v118 offset:4672
	ds_read_b128 v[108:111], v118 offset:6976
	v_mfma_f32_16x16x32_bf16 v[132:135], v[72:75], v[40:43], v[68:71]
	s_nop 0
	v_mfma_f32_16x16x32_bf16 v[72:75], v[72:75], v[36:39], v[64:67]
	s_nop 2
	ds_read_b128 v[64:67], v118 offset:2304
	s_waitcnt lgkmcnt(0)
	v_mfma_f32_16x16x32_bf16 v[68:71], v[64:67], v[44:47], 0
	v_mfma_f32_16x16x32_bf16 v[64:67], v[64:67], v[32:35], 0
	v_mfma_f32_16x16x32_bf16 v[88:91], v[76:79], v[40:43], v[68:71]
	v_mfma_f32_16x16x32_bf16 v[76:79], v[76:79], v[36:39], v[64:67]
	s_nop 5
	ds_read_b128 v[64:67], v118 offset:4608
	s_waitcnt lgkmcnt(0)
	v_mfma_f32_16x16x32_bf16 v[68:71], v[64:67], v[44:47], 0
	v_mfma_f32_16x16x32_bf16 v[64:67], v[64:67], v[32:35], 0
	v_mfma_f32_16x16x32_bf16 v[84:87], v[80:83], v[40:43], v[68:71]
	v_mfma_f32_16x16x32_bf16 v[68:71], v[80:83], v[36:39], v[64:67]
	s_nop 5
	ds_read_b128 v[64:67], v118 offset:6912
	s_waitcnt lgkmcnt(0)
	v_mfma_f32_16x16x32_bf16 v[80:83], v[64:67], v[44:47], 0
	v_mfma_f32_16x16x32_bf16 v[64:67], v[64:67], v[32:35], 0
	v_mfma_f32_16x16x32_bf16 v[80:83], v[108:111], v[40:43], v[80:83]
	v_mfma_f32_16x16x32_bf16 v[64:67], v[108:111], v[36:39], v[64:67]
	v_add_u32_e32 v110, s89, v121
	v_subrev_u32_e32 v108, 64, v110
	v_sub_u32_e32 v109, 64, v110
	v_max_i32_e32 v108, v108, v109
	v_cvt_f32_u32_e32 v100, v108
	v_cmp_gt_u32_e32 vcc, s94, v108
	s_and_b64 s[62:63], s[4:5], vcc
	s_and_b64 vcc, s[62:63], s[6:7]
	v_mul_f32_e32 v108, v101, v100
	v_fma_f32 v100, v132, s95, -v108
	v_subrev_u32_e32 v109, 63, v110
	v_sub_u32_e32 v111, 63, v110
	v_cndmask_b32_e32 v132, v190, v100, vcc
	v_subrev_u32_e32 v100, 63, v131
	v_max_i32_e32 v109, v109, v111
	v_cmp_gt_i32_e64 s[8:9], s50, v100
	v_cvt_f32_u32_e32 v100, v109
	v_subrev_u32_e32 v111, 62, v110
	v_sub_u32_e32 v112, 62, v110
	v_cmp_gt_u32_e32 vcc, s94, v109
	v_subrev_u32_e32 v109, 62, v131
	v_max_i32_e32 v111, v111, v112
	v_cmp_gt_i32_e64 s[10:11], s50, v109
	v_cvt_f32_u32_e32 v109, v111
	s_and_b64 s[64:65], s[4:5], vcc
	v_mul_f32_e32 v127, v101, v100
	s_and_b64 vcc, s[64:65], s[8:9]
	v_fma_f32 v100, v133, s95, -v127
	v_cndmask_b32_e32 v133, v190, v100, vcc
	v_cmp_gt_u32_e32 vcc, s94, v111
	s_and_b64 s[66:67], s[4:5], vcc
	v_mul_f32_e32 v128, v101, v109
	s_and_b64 vcc, s[66:67], s[10:11]
	v_fma_f32 v109, v134, s95, -v128
	v_subrev_u32_e32 v111, 61, v110
	v_sub_u32_e32 v112, 61, v110
	v_cndmask_b32_e32 v134, v190, v109, vcc
	v_subrev_u32_e32 v109, 61, v131
	v_max_i32_e32 v111, v111, v112
	v_cmp_gt_i32_e64 s[12:13], s50, v109
	v_cvt_f32_u32_e32 v109, v111
	v_cmp_gt_u32_e32 vcc, s94, v111
	s_and_b64 s[68:69], s[4:5], vcc
	s_and_b64 vcc, s[68:69], s[12:13]
	v_mul_f32_e32 v129, v101, v109
	v_fma_f32 v109, v135, s95, -v129
	v_subrev_u32_e32 v111, 48, v110
	v_sub_u32_e32 v112, 48, v110
	v_cndmask_b32_e32 v135, v190, v109, vcc
	v_subrev_u32_e32 v109, 48, v131
	v_max_i32_e32 v111, v111, v112
	v_cmp_gt_i32_e64 s[14:15], s50, v109
	v_cvt_f32_u32_e32 v109, v111
	v_cmp_gt_u32_e32 vcc, s94, v111
	v_subrev_u32_e32 v111, 47, v110
	v_sub_u32_e32 v112, 47, v110
	v_mul_f32_e32 v130, v101, v109
	v_subrev_u32_e32 v109, 47, v131
	v_max_i32_e32 v111, v111, v112
	v_cmp_gt_i32_e64 s[16:17], s50, v109
	v_cvt_f32_u32_e32 v109, v111
	s_and_b64 s[70:71], s[4:5], vcc
	s_and_b64 vcc, s[70:71], s[14:15]
	v_fma_f32 v88, v88, s95, -v130
	v_cndmask_b32_e32 v88, v190, v88, vcc
	v_cmp_gt_u32_e32 vcc, s94, v111
	s_and_b64 s[72:73], s[4:5], vcc
	v_mul_f32_e32 v111, v101, v109
	s_and_b64 vcc, s[72:73], s[16:17]
	v_fma_f32 v89, v89, s95, -v111
	v_subrev_u32_e32 v111, 46, v110
	v_sub_u32_e32 v112, 46, v110
	v_cndmask_b32_e32 v136, v190, v89, vcc
	v_subrev_u32_e32 v89, 46, v131
	v_max_i32_e32 v111, v111, v112
	v_cmp_gt_i32_e64 s[18:19], s50, v89
	v_cvt_f32_u32_e32 v89, v111
	v_cmp_gt_u32_e32 vcc, s94, v111
	v_subrev_u32_e32 v112, 45, v110
	v_sub_u32_e32 v113, 45, v110
	v_mul_f32_e32 v111, v101, v89
	v_fma_f32 v90, v90, s95, -v111
	v_subrev_u32_e32 v111, 45, v131
	v_max_i32_e32 v112, v112, v113
	v_cmp_gt_i32_e64 s[20:21], s50, v111
	v_cvt_f32_u32_e32 v111, v112
	s_and_b64 s[74:75], s[4:5], vcc
	s_and_b64 vcc, s[74:75], s[18:19]
	v_cndmask_b32_e32 v90, v190, v90, vcc
	v_cmp_gt_u32_e32 vcc, s94, v112
	v_max3_f32 v100, v132, s90, v133
; template <int DH, int KT, int NQT, bool PF, class Ctx>
; __device__ __forceinline__ void attn_item(unsigned char* smem, const Ctx& c) {
;     ...
;           for (int k4 = 0; k4 < NK4; ++k4)
; #pragma unroll
;             for (int j = 0; j < 4; ++j) { const float v = c.score(t, wid, qt * 16 + l15, 16 * k4 + 4 * quad + j, s[q][k4][j]); s[q][k4][j] = v; mx = fmaxf(mx, v); }
;           mx = fmaxf(mx, __shfl_xor(mx, 16)); mx = fmaxf(mx, __shfl_xor(mx, 32));
;           const float mnew = fmaxf(mrow[qt], mx);
;           if (__any(mnew > mrow[qt])) {
;             const float alpha = __builtin_amdgcn_exp2f(mrow[qt] - mnew);
;             mrow[qt] = mnew;
;             lrow[qt] *= alpha;
; #pragma unroll
;             for (int dt = 0; dt < NDT; ++dt) o[qt][dt] *= alpha;
;           }
	s_and_b64 s[76:77], s[4:5], vcc
	v_mul_f32_e32 v112, v101, v111
	v_max3_f32 v100, v100, v134, v135
	s_and_b64 vcc, s[76:77], s[20:21]
	v_fma_f32 v91, v91, s95, -v112
	v_max3_f32 v100, v100, v88, v136
	v_cndmask_b32_e32 v137, v190, v91, vcc
	v_max3_f32 v112, v100, v90, v137
	v_subrev_u32_e32 v100, 32, v110
	v_sub_u32_e32 v113, 32, v110
	v_subrev_u32_e32 v91, 32, v131
	v_max_i32_e32 v100, v100, v113
	v_cmp_gt_i32_e64 s[22:23], s50, v91
	v_cvt_f32_u32_e32 v91, v100
	v_cmp_gt_u32_e32 vcc, s94, v100
	v_sub_u32_e32 v113, 31, v110
	s_and_b64 s[78:79], s[4:5], vcc
	v_mul_f32_e32 v100, v101, v91
	v_fma_f32 v84, v84, s95, -v100
	v_subrev_u32_e32 v100, 31, v110
	v_max_i32_e32 v100, v100, v113
	v_cvt_f32_u32_e32 v193, v100
	s_and_b64 vcc, s[78:79], s[22:23]
	v_cndmask_b32_e32 v138, v190, v84, vcc
	v_subrev_u32_e32 v84, 31, v131
	v_cmp_gt_u32_e32 vcc, s94, v100
	v_mov_b32_e32 v100, v85
	v_cmp_gt_i32_e64 s[24:25], s50, v84
	v_pk_mul_f32 v[84:85], v[100:101], v[192:193]
	s_and_b64 s[80:81], s[4:5], vcc
	v_sub_f32_e32 v84, v84, v85
	v_subrev_u32_e32 v85, 30, v110
	v_sub_u32_e32 v100, 30, v110
	s_and_b64 vcc, s[80:81], s[24:25]
	v_max_i32_e32 v85, v85, v100
	v_cndmask_b32_e32 v139, v190, v84, vcc
	v_cmp_gt_u32_e32 vcc, s94, v85
	v_cvt_f32_u32_e32 v85, v85
	v_subrev_u32_e32 v84, 30, v131
	v_cmp_gt_i32_e64 s[26:27], s50, v84
	v_mov_b32_e32 v100, v86
	v_mov_b32_e32 v84, v192
	v_max3_f32 v142, v112, v138, v139
	v_pk_mul_f32 v[112:113], v[100:101], v[84:85]
	v_subrev_u32_e32 v100, 29, v110
	v_sub_f32_e32 v86, v112, v113
	v_sub_u32_e32 v112, 29, v110
	v_max_i32_e32 v100, v100, v112
	v_cvt_f32_u32_e32 v113, v100
	s_and_b64 s[82:83], s[4:5], vcc
	s_and_b64 vcc, s[82:83], s[26:27]
	v_cndmask_b32_e32 v140, v190, v86, vcc
	v_subrev_u32_e32 v86, 29, v131
	v_cmp_gt_u32_e32 vcc, s94, v100
	v_mov_b32_e32 v100, v87
	v_mov_b32_e32 v112, v192
	v_cmp_gt_i32_e64 s[28:29], s50, v86
	v_pk_mul_f32 v[86:87], v[100:101], v[112:113]
	s_and_b64 s[84:85], s[4:5], vcc
	v_sub_f32_e32 v86, v86, v87
	v_add_u32_e32 v87, -16, v110
	v_sub_u32_e32 v100, 16, v110
	s_and_b64 vcc, s[84:85], s[28:29]
	v_max_i32_e32 v87, v87, v100
	v_cndmask_b32_e32 v141, v190, v86, vcc
	v_cmp_gt_u32_e32 vcc, s94, v87
	v_cvt_f32_u32_e32 v87, v87
	v_add_u32_e32 v86, -16, v131
	v_cmp_gt_i32_e64 s[30:31], s50, v86
	v_mov_b32_e32 v100, v80
	v_mov_b32_e32 v86, v192
	v_pk_mul_f32 v[86:87], v[100:101], v[86:87]
	s_and_b64 s[34:35], s[4:5], vcc
	v_sub_f32_e32 v80, v86, v87
	v_add_u32_e32 v86, -15, v110
	v_sub_u32_e32 v87, 15, v110
	v_max_i32_e32 v86, v86, v87
	v_cvt_f32_u32_e32 v87, v86
	s_and_b64 vcc, s[34:35], s[30:31]
	v_max3_f32 v144, v142, v140, v141
	v_cndmask_b32_e32 v142, v190, v80, vcc
	v_add_u32_e32 v80, -15, v131
	v_cmp_gt_u32_e32 vcc, s94, v86
	v_mov_b32_e32 v100, v81
	v_mov_b32_e32 v86, v192
	v_cmp_gt_i32_e64 s[34:35], s50, v80
	v_pk_mul_f32 v[80:81], v[100:101], v[86:87]
	s_and_b64 s[36:37], s[4:5], vcc
	v_sub_f32_e32 v80, v80, v81
	v_add_u32_e32 v81, -14, v110
	v_sub_u32_e32 v87, 14, v110
	s_and_b64 vcc, s[36:37], s[34:35]
	v_max_i32_e32 v81, v81, v87
	v_cndmask_b32_e32 v143, v190, v80, vcc
	v_cmp_gt_u32_e32 vcc, s94, v81
	v_cvt_f32_u32_e32 v81, v81
	v_add_u32_e32 v80, -14, v131
	v_cmp_gt_i32_e64 s[36:37], s50, v80
	v_mov_b32_e32 v100, v82
	v_mov_b32_e32 v80, v192
	v_pk_mul_f32 v[80:81], v[100:101], v[80:81]
	s_and_b64 s[38:39], s[4:5], vcc
	v_sub_f32_e32 v80, v80, v81
	v_add_u32_e32 v81, -13, v110
	v_sub_u32_e32 v82, 13, v110
	s_and_b64 vcc, s[38:39], s[36:37]
	v_max_i32_e32 v81, v81, v82
	v_max3_f32 v86, v144, v142, v143
	v_cndmask_b32_e32 v144, v190, v80, vcc
	v_cmp_gt_u32_e32 vcc, s94, v81
	v_cvt_f32_u32_e32 v81, v81
	v_add_u32_e32 v80, -13, v131
	v_cmp_gt_i32_e64 s[38:39], s50, v80
	v_mov_b32_e32 v100, v83
	v_mov_b32_e32 v80, v192
	s_and_b64 vcc, s[4:5], vcc
	v_pk_mul_f32 v[80:81], v[100:101], v[80:81]
	s_and_b64 vcc, vcc, s[38:39]
	v_sub_f32_e32 v80, v80, v81
	v_cndmask_b32_e32 v100, v190, v80, vcc
	v_max3_f32 v80, v86, v144, v100
	ds_bpermute_b32 v81, v125, v80
	s_waitcnt lgkmcnt(0)
	v_max_f32_e32 v81, v81, v81
	v_max_f32_e32 v80, v80, v81
	ds_bpermute_b32 v81, v126, v80
	s_waitcnt lgkmcnt(0)
	v_max3_f32 v80, v98, v80, v81
	v_cmp_gt_f32_e32 vcc, v80, v98
	s_cbranch_vccz .LBB0_183
	v_sub_f32_e32 v81, v98, v80
	v_exp_f32_e32 v82, v81
	v_mov_b32_e32 v81, v99
	v_mov_b64_e32 v[98:99], v[80:81]
	v_mul_f32_e32 v96, v96, v82
	v_pk_mul_f32 v[30:31], v[30:31], v[82:83] op_sel_hi:[1,0]
	v_pk_mul_f32 v[28:29], v[28:29], v[82:83] op_sel_hi:[1,0]
	v_pk_mul_f32 v[14:15], v[14:15], v[82:83] op_sel_hi:[1,0]
	v_pk_mul_f32 v[12:13], v[12:13], v[82:83] op_sel_hi:[1,0]
	v_pk_mul_f32 v[18:19], v[18:19], v[82:83] op_sel_hi:[1,0]
	v_pk_mul_f32 v[16:17], v[16:17], v[82:83] op_sel_hi:[1,0]
	v_pk_mul_f32 v[22:23], v[22:23], v[82:83] op_sel_hi:[1,0]
	v_pk_mul_f32 v[20:21], v[20:21], v[82:83] op_sel_hi:[1,0]

; __device__ __forceinline__ unsigned cvtpk(float lo, float hi) { f32x2_t v = {lo, hi}; bf16x2_t b = __builtin_convertvector(v, bf16x2_t); return __builtin_bit_cast(unsigned, b); }
; template <int DH, int KT, int NQT, bool PF, class Ctx>
; __device__ __forceinline__ void attn_item(unsigned char* smem, const Ctx& c) {
;     ...
;           float psum = 0.f;
; #pragma unroll
;           for (int k4 = 0; k4 < NK4; ++k4)
; #pragma unroll
;             for (int j = 0; j < 4; ++j) { const float pv = __builtin_amdgcn_exp2f(s[q][k4][j] - mnew); s[q][k4][j] = pv; psum += pv; }
;           lrow[qt] += psum;
; #pragma unroll
;           for (int kk = 0; kk < NKK; ++kk) {
;             u32x4 w;
;             w.x = cvtpk(s[q][2 * kk][0], s[q][2 * kk][1]); w.y = cvtpk(s[q][2 * kk][2], s[q][2 * kk][3]);
;             w.z = cvtpk(s[q][2 * kk + 1][0], s[q][2 * kk + 1][1]); w.w = cvtpk(s[q][2 * kk + 1][2], s[q][2 * kk + 1][3]);
;             pfa[qt][kk] = __builtin_bit_cast(bf16x8, w);
;           }
;         }
;       }
; #pragma unroll
;       for (int kk = 0; kk < NKK; ++kk) {
;         const bf16_t* vb = sV + (32 * kk + 4 * quad + (l15 >> 2)) * LDK + 4 * (l15 & 3);
; #pragma unroll
;         for (int dt = 0; dt < NDT; ++dt) {
;           const s16x4 lo = tr_read(vb + 16 * dt);
;           const s16x4 hi = tr_read(vb + 16 * LDK + 16 * dt);
;           const bf16x8 vf = (bf16x8){lo[0], lo[1], lo[2], lo[3], hi[0], hi[1], hi[2], hi[3]};
; #pragma unroll
;           for (int qt = 0; qt < NQT; ++qt) o[qt][dt] = __builtin_amdgcn_mfma_f32_16x16x32_bf16(vf, pfa[qt][kk], o[qt][dt], 0, 0, 0);
;         }
;       }
.LBB0_212:
	s_setprio 0
	v_mov_b32_e32 v249, 0
	v_exp_f32_e32 v169, v184
	v_exp_f32_e32 v170, v185
	v_exp_f32_e32 v171, v186
	v_exp_f32_e32 v173, v187
	v_add_f32_e32 v174, 0, v169
	v_exp_f32_e32 v175, v176
	v_add_f32_e32 v174, v170, v174
	v_exp_f32_e32 v176, v177
	v_add_f32_e32 v174, v171, v174
	v_exp_f32_e32 v177, v178
	v_add_f32_e32 v174, v173, v174
	v_exp_f32_e32 v178, v179
	v_add_f32_e32 v174, v175, v174
	v_exp_f32_e32 v179, v164
	v_add_f32_e32 v174, v176, v174
	v_exp_f32_e32 v180, v165
	v_add_f32_e32 v174, v177, v174
	v_exp_f32_e32 v181, v166
	v_add_f32_e32 v174, v178, v174
	v_exp_f32_e32 v182, v167
	v_add_f32_e32 v164, v179, v174
	v_exp_f32_e32 v174, v156
	v_exp_f32_e32 v144, v144
	v_add_f32_e32 v164, v180, v164
	v_exp_f32_e32 v145, v145
	v_add_f32_e32 v164, v181, v164
	v_exp_f32_e32 v183, v157
	v_exp_f32_e32 v146, v146
	v_add_f32_e32 v164, v182, v164
	v_exp_f32_e32 v184, v158
	v_exp_f32_e32 v147, v147
	v_exp_f32_e32 v159, v159
	v_add_f32_e32 v156, v174, v164
	v_cvt_pk_bf16_f32 v164, v169, v170
	v_add_f32_e32 v169, 0, v144
	v_exp_f32_e32 v140, v140
	v_add_f32_e32 v169, v145, v169
	v_exp_f32_e32 v141, v141
	v_add_f32_e32 v169, v146, v169
	v_exp_f32_e32 v142, v142
	v_add_f32_e32 v169, v147, v169
	v_exp_f32_e32 v143, v143
	v_add_f32_e32 v169, v140, v169
	v_exp_f32_e32 v152, v152
	v_add_f32_e32 v169, v141, v169
	v_exp_f32_e32 v153, v153
	v_add_f32_e32 v169, v142, v169
	v_exp_f32_e32 v154, v154
	v_add_f32_e32 v169, v143, v169
	v_exp_f32_e32 v155, v155
	v_add_f32_e32 v169, v152, v169
	v_exp_f32_e32 v170, v148
	v_add_f32_e32 v169, v153, v169
	v_cvt_pk_bf16_f32 v165, v171, v173
	v_add_f32_e32 v169, v154, v169
	v_exp_f32_e32 v171, v149
	v_add_f32_e32 v169, v155, v169
	v_exp_f32_e32 v172, v150
	v_exp_f32_e32 v173, v151
	v_add_f32_e32 v148, v170, v169
	v_exp_f32_e32 v169, v128
	v_cvt_pk_bf16_f32 v158, v174, v183
	v_exp_f32_e32 v174, v129
	v_cvt_pk_bf16_f32 v166, v175, v176
	v_exp_f32_e32 v175, v130
	v_add_f32_e32 v156, v183, v156
	v_exp_f32_e32 v176, v131
	v_add_f32_e32 v156, v184, v156
	v_cvt_pk_bf16_f32 v167, v177, v178
	v_cvt_pk_bf16_f32 v157, v181, v182
	v_exp_f32_e32 v177, v124
	v_exp_f32_e32 v181, v160
	v_exp_f32_e32 v185, v136
	v_add_f32_e32 v156, v159, v156
	v_add_f32_e32 v148, v171, v148
	v_exp_f32_e32 v178, v125
	v_exp_f32_e32 v182, v161
	v_exp_f32_e32 v186, v137
	v_add_f32_e32 v193, v156, v193
	v_cvt_pk_bf16_f32 v156, v179, v180
	v_add_f32_e32 v148, v172, v148
	v_exp_f32_e32 v179, v126
	v_exp_f32_e32 v183, v162
	v_exp_f32_e32 v187, v138
	v_cvt_pk_bf16_f32 v159, v184, v159
	v_add_f32_e32 v148, v173, v148
	v_exp_f32_e32 v180, v127
	v_exp_f32_e32 v184, v163
	v_exp_f32_e32 v231, v139
	v_add_f32_e32 v218, v148, v218
	v_cvt_pk_bf16_f32 v144, v144, v145
	v_cvt_pk_bf16_f32 v145, v146, v147
	v_cvt_pk_bf16_f32 v146, v140, v141
	v_cvt_pk_bf16_f32 v147, v142, v143
	v_cvt_pk_bf16_f32 v140, v152, v153
	v_cvt_pk_bf16_f32 v141, v154, v155
	ds_read_b64_tr_b16 v[130:131], v224 offset:11520
	ds_read_b64_tr_b16 v[128:129], v224 offset:9216
	ds_read_b64_tr_b16 v[148:149], v224 offset:9248
	ds_read_b64_tr_b16 v[152:153], v224 offset:9280
	ds_read_b64_tr_b16 v[160:161], v224 offset:9312
	ds_read_b64_tr_b16 v[150:151], v224 offset:11552
	ds_read_b64_tr_b16 v[154:155], v224 offset:11584
	ds_read_b64_tr_b16 v[162:163], v224 offset:11616
	v_cvt_pk_bf16_f32 v142, v170, v171
	v_exp_f32_e32 v170, v112
	v_exp_f32_e32 v171, v113
	v_cvt_pk_bf16_f32 v143, v172, v173
	v_exp_f32_e32 v172, v114
	v_cvt_pk_bf16_f32 v124, v169, v174
	v_cvt_pk_bf16_f32 v125, v175, v176
	v_cvt_pk_bf16_f32 v126, v177, v178
	v_cvt_pk_bf16_f32 v127, v179, v180
	v_cvt_pk_bf16_f32 v136, v181, v182
	v_cvt_pk_bf16_f32 v137, v183, v184
	v_cvt_pk_bf16_f32 v138, v185, v186
	v_cvt_pk_bf16_f32 v139, v187, v231
	v_exp_f32_e32 v173, v115
	s_waitcnt lgkmcnt(1)
	v_mfma_f32_16x16x32_bf16 v[100:103], v[152:155], v[124:127], v[100:103]
	v_add_f32_e32 v169, 0, v169
	v_cvt_pk_bf16_f32 v113, v172, v173
	s_add_u32 s4, s4, 0x60000
	v_mfma_f32_16x16x32_bf16 v[84:87], v[152:155], v[144:147], v[84:87]
	s_addc_u32 s5, s5, 0
	s_add_i32 s7, s7, 1
	s_cmp_lg_u32 s8, s4
	v_mfma_f32_16x16x32_bf16 v[52:55], v[152:155], v[164:167], v[52:55]
	v_mfma_f32_16x16x32_bf16 v[12:15], v[152:155], v[136:139], v[12:15]
	v_exp_f32_e32 v152, v132
	v_exp_f32_e32 v153, v133
	v_exp_f32_e32 v154, v134
	v_mfma_f32_16x16x32_bf16 v[92:95], v[128:131], v[144:147], v[92:95]
	v_mfma_f32_16x16x32_bf16 v[104:107], v[148:151], v[124:127], v[104:107]
	v_mfma_f32_16x16x32_bf16 v[88:91], v[148:151], v[144:147], v[88:91]
	v_mfma_f32_16x16x32_bf16 v[64:67], v[148:151], v[164:167], v[64:67]
	v_mfma_f32_16x16x32_bf16 v[24:27], v[148:151], v[136:139], v[24:27]
	v_exp_f32_e32 v148, v116
	v_exp_f32_e32 v149, v117
	s_waitcnt lgkmcnt(0)
; template <int DH, int KT, int NQT, bool PF, class Ctx>
; __device__ __forceinline__ void attn_item(unsigned char* smem, const Ctx& c) {
;     ...
;     __syncthreads();
;     if constexpr (PF) {
;       static_assert(!PF || NCH == 2 || NCH == 4, "wait lists below are written for two or four chunks per matrix");
;       if constexpr (NCH == 2) asm volatile("s_waitcnt vmcnt(0)" : "+v"(rk[0]), "+v"(rk[NCH - 1]), "+v"(rv[0]), "+v"(rv[NCH - 1]) :: "memory");
;       else asm volatile("s_waitcnt vmcnt(0)" : "+v"(rk[0]), "+v"(rk[1]), "+v"(rk[NCH - 2]), "+v"(rk[NCH - 1]), "+v"(rv[0]), "+v"(rv[1]), "+v"(rv[NCH - 2]), "+v"(rv[NCH - 1]) :: "memory");
; #pragma unroll
;       for (int i = 0; i < NCH; ++i) {
;         const int ci = tid + 256 * i, row = ci / CH, ch = ci % CH;
;         *(u32x4*)(sK + row * LDK + ch * 8) = rk[i]; *(u32x4*)(sV + row * LDK + ch * 8) = rv[i];
;       }
;     } else {
; #pragma unroll
;       for (int i = 0; i < NCH; ++i) {
;         const int ci = tid + 256 * i, row = ci / CH, ch = ci % CH;
;         *(u32x4*)(sK + row * LDK + ch * 8) = ld_agent_u32x4(c.kptr(t, row) + ch * 8);
;     ...
;           float psum = 0.f;
; #pragma unroll
;           for (int k4 = 0; k4 < NK4; ++k4)
; #pragma unroll
;             for (int j = 0; j < 4; ++j) { const float pv = __builtin_amdgcn_exp2f(s[q][k4][j] - mnew); s[q][k4][j] = pv; psum += pv; }
;           lrow[qt] += psum;
; #pragma unroll
;           for (int kk = 0; kk < NKK; ++kk) {
;             u32x4 w;
;             w.x = cvtpk(s[q][2 * kk][0], s[q][2 * kk][1]); w.y = cvtpk(s[q][2 * kk][2], s[q][2 * kk][3]);
;             w.z = cvtpk(s[q][2 * kk + 1][0], s[q][2 * kk + 1][1]); w.w = cvtpk(s[q][2 * kk + 1][2], s[q][2 * kk + 1][3]);
;             pfa[qt][kk] = __builtin_bit_cast(bf16x8, w);
;           }
;         }
;       }
; #pragma unroll
;       for (int kk = 0; kk < NKK; ++kk) {
;         const bf16_t* vb = sV + (32 * kk + 4 * quad + (l15 >> 2)) * LDK + 4 * (l15 & 3);
; #pragma unroll
;         for (int dt = 0; dt < NDT; ++dt) {
;           const s16x4 lo = tr_read(vb + 16 * dt);
;           const s16x4 hi = tr_read(vb + 16 * LDK + 16 * dt);
;           const bf16x8 vf = (bf16x8){lo[0], lo[1], lo[2], lo[3], hi[0], hi[1], hi[2], hi[3]};
; #pragma unroll
;           for (int qt = 0; qt < NQT; ++qt) o[qt][dt] = __builtin_amdgcn_mfma_f32_16x16x32_bf16(vf, pfa[qt][kk], o[qt][dt], 0, 0, 0);
;         }
;       }
	v_mfma_f32_16x16x32_bf16 v[68:71], v[160:163], v[144:147], v[68:71]
	v_exp_f32_e32 v144, v135
	v_mfma_f32_16x16x32_bf16 v[32:35], v[128:131], v[136:139], v[32:35]
	v_exp_f32_e32 v150, v118
	v_mfma_f32_16x16x32_bf16 v[0:3], v[160:163], v[136:139], v[0:3]
	v_exp_f32_e32 v136, v121
	v_exp_f32_e32 v137, v122
	v_exp_f32_e32 v151, v119
	v_exp_f32_e32 v145, v120
	ds_read_b64_tr_b16 v[116:117], v224 offset:13824
	ds_read_b64_tr_b16 v[118:119], v224 offset:16128
	v_exp_f32_e32 v138, v123
	v_mfma_f32_16x16x32_bf16 v[108:111], v[128:131], v[124:127], v[108:111]
	v_cvt_pk_bf16_f32 v112, v170, v171
	v_cvt_pk_bf16_f32 v114, v148, v149
	v_cvt_pk_bf16_f32 v115, v150, v151
	v_mfma_f32_16x16x32_bf16 v[76:79], v[128:131], v[164:167], v[76:79]
	v_cvt_pk_bf16_f32 v120, v152, v153
	v_cvt_pk_bf16_f32 v121, v154, v144
	v_cvt_pk_bf16_f32 v122, v145, v136
	v_cvt_pk_bf16_f32 v123, v137, v138
	s_waitcnt lgkmcnt(0)
	v_mfma_f32_16x16x32_bf16 v[108:111], v[116:119], v[112:115], v[108:111]
	v_mfma_f32_16x16x32_bf16 v[92:95], v[116:119], v[140:143], v[92:95]
	v_mfma_f32_16x16x32_bf16 v[76:79], v[116:119], v[156:159], v[76:79]
	v_mfma_f32_16x16x32_bf16 v[32:35], v[116:119], v[120:123], v[32:35]
	v_add_f32_e32 v116, v174, v169
	v_add_f32_e32 v116, v175, v116
	v_add_f32_e32 v116, v176, v116
	v_add_f32_e32 v116, v177, v116
	v_add_f32_e32 v116, v178, v116
	v_add_f32_e32 v116, v179, v116
	v_add_f32_e32 v116, v180, v116
	v_add_f32_e32 v116, v170, v116
	v_add_f32_e32 v116, v171, v116
	v_add_f32_e32 v116, v172, v116
	v_add_f32_e32 v116, v173, v116
	v_add_f32_e32 v116, v148, v116
	v_add_f32_e32 v116, v149, v116
	v_add_f32_e32 v116, v150, v116
	v_add_f32_e32 v116, v151, v116
	v_add_f32_e32 v225, v116, v225
	v_add_f32_e32 v116, 0, v181
	v_add_f32_e32 v116, v182, v116
	v_add_f32_e32 v116, v183, v116
	v_add_f32_e32 v116, v184, v116
	v_add_f32_e32 v116, v185, v116
	v_add_f32_e32 v116, v186, v116
	v_mfma_f32_16x16x32_bf16 v[96:99], v[160:163], v[124:127], v[96:99]
	ds_read_b64_tr_b16 v[124:125], v224 offset:13856
	ds_read_b64_tr_b16 v[128:129], v224 offset:13888
	ds_read_b64_tr_b16 v[132:133], v224 offset:13920
	ds_read_b64_tr_b16 v[126:127], v224 offset:16160
	ds_read_b64_tr_b16 v[130:131], v224 offset:16192
	ds_read_b64_tr_b16 v[134:135], v224 offset:16224
	v_add_f32_e32 v116, v187, v116
	v_add_f32_e32 v116, v231, v116
	v_add_f32_e32 v116, v152, v116
	v_mfma_f32_16x16x32_bf16 v[48:51], v[160:163], v[164:167], v[48:51]
	v_add_f32_e32 v116, v153, v116
	v_add_f32_e32 v116, v154, v116
	s_waitcnt lgkmcnt(2)
	v_mfma_f32_16x16x32_bf16 v[104:107], v[124:127], v[112:115], v[104:107]
	s_waitcnt lgkmcnt(1)
	v_mfma_f32_16x16x32_bf16 v[100:103], v[128:131], v[112:115], v[100:103]
	s_waitcnt lgkmcnt(0)
	v_mfma_f32_16x16x32_bf16 v[96:99], v[132:135], v[112:115], v[96:99]
	v_add_f32_e32 v112, v144, v116
	v_add_f32_e32 v112, v145, v112
	v_add_f32_e32 v112, v136, v112
	v_mfma_f32_16x16x32_bf16 v[88:91], v[124:127], v[140:143], v[88:91]
	v_add_f32_e32 v112, v137, v112
	v_add_f32_e32 v112, v138, v112
	v_add_f32_e32 v191, v112, v191
	v_mfma_f32_16x16x32_bf16 v[64:67], v[124:127], v[156:159], v[64:67]
	v_mfma_f32_16x16x32_bf16 v[24:27], v[124:127], v[120:123], v[24:27]
	v_mfma_f32_16x16x32_bf16 v[84:87], v[128:131], v[140:143], v[84:87]
	v_mfma_f32_16x16x32_bf16 v[52:55], v[128:131], v[156:159], v[52:55]
	v_mfma_f32_16x16x32_bf16 v[12:15], v[128:131], v[120:123], v[12:15]
	v_mfma_f32_16x16x32_bf16 v[68:71], v[132:135], v[140:143], v[68:71]
	v_mfma_f32_16x16x32_bf16 v[48:51], v[132:135], v[156:159], v[48:51]
	v_mfma_f32_16x16x32_bf16 v[0:3], v[132:135], v[120:123], v[0:3]
	s_setprio 0
	s_cbranch_scc0 .LBB0_174
.LBB0_213:
	s_setprio 1
	v_xor_b32_e32 v221, 0x8000, v221
	v_xor_b32_e32 v222, 0x8000, v222
	v_xor_b32_e32 v188, 0x8000, v188
	v_xor_b32_e32 v224, 0x8000, v224
	s_waitcnt vmcnt(0)
	s_cmp_ge_u32 s7, s6
	ds_write_b128 v221, v[56:59]
	ds_write_b128 v221, v[60:63] offset:9216
	ds_write_b128 v222, v[72:75]
	ds_write_b128 v222, v[80:83] offset:9216
	s_waitcnt lgkmcnt(0)
	s_barrier
	s_cbranch_scc1 .LBB0_215
	v_lshl_add_u64 v[56:57], v[208:209], 0, s[4:5]
	v_lshl_add_u64 v[60:61], v[202:203], 1, v[56:57]
	v_lshl_add_u64 v[56:57], v[60:61], 0, s[52:53]
	v_lshl_add_u64 v[72:73], v[206:207], 0, s[4:5]
	global_load_dwordx4 v[56:59], v[56:57], off sc1
	v_lshl_add_u64 v[60:61], v[60:61], 0, s[54:55]
	v_lshl_add_u64 v[80:81], v[204:205], 1, v[72:73]
	global_load_dwordx4 v[60:63], v[60:61], off sc1
	v_lshl_add_u64 v[72:73], v[80:81], 0, s[52:53]
	global_load_dwordx4 v[72:75], v[72:73], off sc1
	v_lshl_add_u64 v[80:81], v[80:81], 0, s[54:55]
	global_load_dwordx4 v[80:83], v[80:81], off sc1

; __device__ __forceinline__ unsigned cvtpk(float lo, float hi) { f32x2_t v = {lo, hi}; bf16x2_t b = __builtin_convertvector(v, bf16x2_t); return __builtin_bit_cast(unsigned, b); }
; template <int DH, int KT, int NQT, bool PF, class Ctx>
; __device__ __forceinline__ void attn_item(unsigned char* smem, const Ctx& c) {
;     ...
;           float psum = 0.f;
; #pragma unroll
;           for (int k4 = 0; k4 < NK4; ++k4)
; #pragma unroll
;             for (int j = 0; j < 4; ++j) { const float pv = __builtin_amdgcn_exp2f(s[q][k4][j] - mnew); s[q][k4][j] = pv; psum += pv; }
;           lrow[qt] += psum;
; #pragma unroll
;           for (int kk = 0; kk < NKK; ++kk) {
;             u32x4 w;
;             w.x = cvtpk(s[q][2 * kk][0], s[q][2 * kk][1]); w.y = cvtpk(s[q][2 * kk][2], s[q][2 * kk][3]);
;             w.z = cvtpk(s[q][2 * kk + 1][0], s[q][2 * kk + 1][1]); w.w = cvtpk(s[q][2 * kk + 1][2], s[q][2 * kk + 1][3]);
;             pfa[qt][kk] = __builtin_bit_cast(bf16x8, w);
;           }
;         }
;       }
; #pragma unroll
;       for (int kk = 0; kk < NKK; ++kk) {
;         const bf16_t* vb = sV + (32 * kk + 4 * quad + (l15 >> 2)) * LDK + 4 * (l15 & 3);
; #pragma unroll
;         for (int dt = 0; dt < NDT; ++dt) {
;           const s16x4 lo = tr_read(vb + 16 * dt);
;           const s16x4 hi = tr_read(vb + 16 * LDK + 16 * dt);
;           const bf16x8 vf = (bf16x8){lo[0], lo[1], lo[2], lo[3], hi[0], hi[1], hi[2], hi[3]};
; #pragma unroll
;           for (int qt = 0; qt < NQT; ++qt) o[qt][dt] = __builtin_amdgcn_mfma_f32_16x16x32_bf16(vf, pfa[qt][kk], o[qt][dt], 0, 0, 0);
;         }
;       }
.LBB0_326:
	s_setprio 0
	v_sub_f32_e32 v163, v163, v170
	v_sub_f32_e32 v169, v169, v170
	v_sub_f32_e32 v168, v168, v170
	v_sub_f32_e32 v167, v167, v170
	v_sub_f32_e32 v166, v166, v170
	v_sub_f32_e32 v165, v165, v170
	v_exp_f32_e32 v187, v163
	v_sub_f32_e32 v163, v164, v170
	v_sub_f32_e32 v162, v162, v170
	v_exp_f32_e32 v182, v169
	v_exp_f32_e32 v183, v168
	v_exp_f32_e32 v184, v167
	v_exp_f32_e32 v185, v166
	v_exp_f32_e32 v186, v165
	v_exp_f32_e32 v188, v163
	v_exp_f32_e32 v189, v162
	ds_read_b64_tr_b16 v[168:169], v153 offset:25344
	ds_read_b64_tr_b16 v[166:167], v153 offset:16896
	v_cvt_pk_bf16_f32 v162, v182, v183
	v_cvt_pk_bf16_f32 v163, v184, v185
	v_cvt_pk_bf16_f32 v164, v186, v187
	v_cvt_pk_bf16_f32 v165, v188, v189
	ds_read_b64_tr_b16 v[172:173], v153 offset:25376
	ds_read_b64_tr_b16 v[170:171], v153 offset:16928
	ds_read_b64_tr_b16 v[174:175], v153 offset:16960
	ds_read_b64_tr_b16 v[178:179], v153 offset:16992
	ds_read_b64_tr_b16 v[176:177], v153 offset:25408
	ds_read_b64_tr_b16 v[180:181], v153 offset:25440
	s_waitcnt lgkmcnt(6)
	v_mfma_f32_16x16x32_bf16 v[60:63], v[166:169], v[162:165], v[60:63]
	ds_read_b64_tr_b16 v[166:167], v153 offset:17024
	ds_read_b64_tr_b16 v[168:169], v153 offset:25472
	s_add_u32 s14, s14, 0x20000
	s_addc_u32 s15, s15, 0
	s_waitcnt lgkmcnt(6)
	v_mfma_f32_16x16x32_bf16 v[56:59], v[170:173], v[162:165], v[56:59]
	s_cmp_eq_u32 s14, 0xe0000
	s_waitcnt lgkmcnt(3)
	v_mfma_f32_16x16x32_bf16 v[52:55], v[174:177], v[162:165], v[52:55]
	s_waitcnt lgkmcnt(2)
	v_mfma_f32_16x16x32_bf16 v[48:51], v[178:181], v[162:165], v[48:51]
	ds_read_b64_tr_b16 v[172:173], v153 offset:25504
	ds_read_b64_tr_b16 v[170:171], v153 offset:17056
	ds_read_b64_tr_b16 v[174:175], v153 offset:17088
	ds_read_b64_tr_b16 v[178:179], v153 offset:17120
	ds_read_b64_tr_b16 v[176:177], v153 offset:25536
	ds_read_b64_tr_b16 v[180:181], v153 offset:25568
	s_waitcnt lgkmcnt(6)
	v_mfma_f32_16x16x32_bf16 v[44:47], v[166:169], v[162:165], v[44:47]
	ds_read_b64_tr_b16 v[166:167], v153 offset:17152
	ds_read_b64_tr_b16 v[168:169], v153 offset:25600
	s_waitcnt lgkmcnt(6)
	v_mfma_f32_16x16x32_bf16 v[40:43], v[170:173], v[162:165], v[40:43]
	s_waitcnt lgkmcnt(3)
	v_mfma_f32_16x16x32_bf16 v[36:39], v[174:177], v[162:165], v[36:39]
	s_waitcnt lgkmcnt(2)
	v_mfma_f32_16x16x32_bf16 v[32:35], v[178:181], v[162:165], v[32:35]
	ds_read_b64_tr_b16 v[172:173], v153 offset:25632
	ds_read_b64_tr_b16 v[170:171], v153 offset:17184
	ds_read_b64_tr_b16 v[174:175], v153 offset:17216
	ds_read_b64_tr_b16 v[178:179], v153 offset:17248
	ds_read_b64_tr_b16 v[176:177], v153 offset:25664
	ds_read_b64_tr_b16 v[180:181], v153 offset:25696
	s_waitcnt lgkmcnt(6)
	v_mfma_f32_16x16x32_bf16 v[28:31], v[166:169], v[162:165], v[28:31]
	ds_read_b64_tr_b16 v[166:167], v153 offset:17280
	ds_read_b64_tr_b16 v[168:169], v153 offset:25728
	s_waitcnt lgkmcnt(6)
	v_mfma_f32_16x16x32_bf16 v[24:27], v[170:173], v[162:165], v[24:27]
	s_waitcnt lgkmcnt(3)
	v_mfma_f32_16x16x32_bf16 v[20:23], v[174:177], v[162:165], v[20:23]
	s_waitcnt lgkmcnt(2)
	v_mfma_f32_16x16x32_bf16 v[16:19], v[178:181], v[162:165], v[16:19]
	ds_read_b64_tr_b16 v[172:173], v153 offset:25760
	ds_read_b64_tr_b16 v[170:171], v153 offset:17312
	ds_read_b64_tr_b16 v[174:175], v153 offset:17344
	ds_read_b64_tr_b16 v[178:179], v153 offset:17376
	ds_read_b64_tr_b16 v[176:177], v153 offset:25792
	ds_read_b64_tr_b16 v[180:181], v153 offset:25824
	s_waitcnt lgkmcnt(6)
	v_mfma_f32_16x16x32_bf16 v[12:15], v[166:169], v[162:165], v[12:15]
	v_add_f32_e32 v166, 0, v182
	v_add_f32_e32 v166, v183, v166
	v_add_f32_e32 v166, v184, v166
	v_add_f32_e32 v166, v185, v166
	s_waitcnt lgkmcnt(4)
	v_mfma_f32_16x16x32_bf16 v[8:11], v[170:173], v[162:165], v[8:11]
	s_waitcnt lgkmcnt(1)
	v_mfma_f32_16x16x32_bf16 v[4:7], v[174:177], v[162:165], v[4:7]
	s_waitcnt lgkmcnt(0)
	v_mfma_f32_16x16x32_bf16 v[0:3], v[178:181], v[162:165], v[0:3]
	v_add_f32_e32 v162, v186, v166
	v_add_f32_e32 v162, v187, v162
	v_add_f32_e32 v162, v188, v162
	v_add_f32_e32 v162, v189, v162
	v_add_f32_e32 v128, v162, v128
	s_cbranch_scc1 .LBB0_329
; __device__ __forceinline__ void ld16_sc1(u32x4& v, const void* p) { asm volatile("global_load_dwordx4 %0, %1, off sc1" : "=v"(v) : "v"(p) : "memory"); }
; template <int DH, int KT, int NQT, bool PF, class Ctx>
; __device__ __forceinline__ void attn_item(unsigned char* smem, const Ctx& c) {
;     ...
;     __syncthreads();
;     if constexpr (PF) {
;       static_assert(!PF || NCH == 2 || NCH == 4, "wait lists below are written for two or four chunks per matrix");
;       if constexpr (NCH == 2) asm volatile("s_waitcnt vmcnt(0)" : "+v"(rk[0]), "+v"(rk[NCH - 1]), "+v"(rv[0]), "+v"(rv[NCH - 1]) :: "memory");
;       else asm volatile("s_waitcnt vmcnt(0)" : "+v"(rk[0]), "+v"(rk[1]), "+v"(rk[NCH - 2]), "+v"(rk[NCH - 1]), "+v"(rv[0]), "+v"(rv[1]), "+v"(rv[NCH - 2]), "+v"(rv[NCH - 1]) :: "memory");
; #pragma unroll
;       for (int i = 0; i < NCH; ++i) {
;         const int ci = tid + 256 * i, row = ci / CH, ch = ci % CH;
;         *(u32x4*)(sK + row * LDK + ch * 8) = rk[i]; *(u32x4*)(sV + row * LDK + ch * 8) = rv[i];
;       }
;     } else {
; #pragma unroll
;       for (int i = 0; i < NCH; ++i) {
;         const int ci = tid + 256 * i, row = ci / CH, ch = ci % CH;
;         *(u32x4*)(sK + row * LDK + ch * 8) = ld_agent_u32x4(c.kptr(t, row) + ch * 8);
;       }
; #pragma unroll
;       for (int i = 0; i < NCH; ++i) {
;         const int ci = tid + 256 * i, row = ci / CH, ch = ci % CH;
;         *(u32x4*)(sV + row * LDK + ch * 8) = ld_agent_u32x4(c.vptr(t, row) + ch * 8);
;       }
;     }
;     __syncthreads();
;     if constexpr (PF) {
;       if (t + 1 < nt) {
; #pragma unroll
;         for (int i = 0; i < NCH; ++i) {
;           const int ci = tid + 256 * i, row = ci / CH, ch = ci % CH;
;           ld16_sc1(rk[i], c.kptr(t + 1, row) + ch * 8); ld16_sc1(rv[i], c.vptr(t + 1, row) + ch * 8);
;         }
;     ...
;         for (int k4 = 0; k4 < NK4; ++k4)
; #pragma unroll
;           for (int ks = 0; ks < NKS; ++ks) {
;             const bf16x8 kf = *(const bf16x8*)(sK + (16 * k4 + l15) * LDK + ks * 32 + quad * 8);
; #pragma unroll
;             for (int q = 0; q < QG; ++q) s[q][k4] = __builtin_amdgcn_mfma_f32_16x16x32_bf16(kf, qf[g + q][ks], s[q][k4], 0, 0, 0);
;           }
; #pragma unroll
;         for (int q = 0; q < QG; ++q) {
;           const int qt = g + q;
;           float mx = -1e30f;
; #pragma unroll
;           for (int k4 = 0; k4 < NK4; ++k4)
; #pragma unroll
.LBB0_327:
	s_setprio 1
	s_barrier
	s_waitcnt vmcnt(0)
	ds_write_b128 v157, v[96:99]
	ds_write_b128 v157, v[100:103] offset:16896
	ds_write_b128 v158, v[104:107]
	ds_write_b128 v158, v[108:111] offset:16896
	ds_write_b128 v159, v[112:115]
	ds_write_b128 v159, v[116:119] offset:16896
	ds_write_b128 v160, v[120:123]
	ds_write_b128 v160, v[124:127] offset:16896
	v_lshl_add_u64 v[96:97], v[146:147], 0, s[14:15]
	v_lshl_add_u64 v[100:101], v[132:133], 1, v[96:97]
	v_lshl_add_u64 v[96:97], v[100:101], 0, s[10:11]
	v_lshl_add_u64 v[104:105], v[144:145], 0, s[14:15]
	s_waitcnt lgkmcnt(0)
	s_barrier
	global_load_dwordx4 v[96:99], v[96:97], off sc1
	v_lshl_add_u64 v[100:101], v[100:101], 0, s[12:13]
	v_lshl_add_u64 v[108:109], v[134:135], 1, v[104:105]
	global_load_dwordx4 v[100:103], v[100:101], off sc1
	v_lshl_add_u64 v[104:105], v[108:109], 0, s[10:11]
	v_lshl_add_u64 v[112:113], v[142:143], 0, s[14:15]
	global_load_dwordx4 v[104:107], v[104:105], off sc1
	v_lshl_add_u64 v[108:109], v[108:109], 0, s[12:13]
	v_lshl_add_u64 v[116:117], v[136:137], 1, v[112:113]
	global_load_dwordx4 v[108:111], v[108:109], off sc1
	v_lshl_add_u64 v[112:113], v[116:117], 0, s[10:11]
	v_lshl_add_u64 v[120:121], v[140:141], 0, s[14:15]
	global_load_dwordx4 v[112:115], v[112:113], off sc1
	v_lshl_add_u64 v[116:117], v[116:117], 0, s[12:13]
	v_lshl_add_u64 v[124:125], v[138:139], 1, v[120:121]
	global_load_dwordx4 v[116:119], v[116:117], off sc1
	v_lshl_add_u64 v[120:121], v[124:125], 0, s[10:11]
	global_load_dwordx4 v[120:123], v[120:121], off sc1
	v_lshl_add_u64 v[124:125], v[124:125], 0, s[12:13]
	global_load_dwordx4 v[124:127], v[124:125], off sc1
	ds_read_b128 v[162:165], v156
	ds_read_b128 v[166:169], v156 offset:64
	s_waitcnt lgkmcnt(1)
	v_mfma_f32_16x16x32_bf16 v[162:165], v[162:165], v[72:75], 0
	ds_read_b128 v[170:173], v156 offset:128
	ds_read_b128 v[174:177], v156 offset:8576
	v_cmp_lt_i32_e32 vcc, v149, v150
	s_waitcnt lgkmcnt(2)
	v_mfma_f32_16x16x32_bf16 v[162:165], v[166:169], v[76:79], v[162:165]
	ds_read_b128 v[166:169], v156 offset:192
	v_cndmask_b32_e32 v154, v148, v149, vcc
	v_lshlrev_b32_e32 v154, 2, v154
	s_waitcnt lgkmcnt(2)
	v_mfma_f32_16x16x32_bf16 v[162:165], v[170:173], v[64:67], v[162:165]
	ds_read_b128 v[170:173], v156 offset:256
	v_cmp_lt_i32_e32 vcc, v151, v150
	s_waitcnt lgkmcnt(1)
	v_mfma_f32_16x16x32_bf16 v[162:165], v[166:169], v[68:71], v[162:165]
	ds_read_b128 v[166:169], v156 offset:320
	s_waitcnt lgkmcnt(1)
	v_mfma_f32_16x16x32_bf16 v[162:165], v[170:173], v[80:83], v[162:165]
	ds_read_b128 v[170:173], v156 offset:384
	s_waitcnt lgkmcnt(1)
	v_mfma_f32_16x16x32_bf16 v[162:165], v[166:169], v[84:87], v[162:165]
	ds_read_b128 v[166:169], v156 offset:448
	s_waitcnt lgkmcnt(1)
	v_mfma_f32_16x16x32_bf16 v[162:165], v[170:173], v[88:91], v[162:165]
	ds_read_b128 v[170:173], v156 offset:8448
	s_waitcnt lgkmcnt(1)
	v_mfma_f32_16x16x32_bf16 v[162:165], v[166:169], v[92:95], v[162:165]
	ds_read_b128 v[166:169], v156 offset:8512
	s_waitcnt lgkmcnt(1)
	v_mfma_f32_16x16x32_bf16 v[170:173], v[170:173], v[72:75], 0
	s_waitcnt lgkmcnt(0)
	v_mfma_f32_16x16x32_bf16 v[166:169], v[166:169], v[76:79], v[170:173]
	s_nop 5
	ds_read_b128 v[170:173], v156 offset:8640
	v_mfma_f32_16x16x32_bf16 v[166:169], v[174:177], v[64:67], v[166:169]
	ds_read_b128 v[174:177], v156 offset:8704
	s_waitcnt lgkmcnt(1)
	v_mfma_f32_16x16x32_bf16 v[166:169], v[170:173], v[68:71], v[166:169]
	ds_read_b128 v[170:173], v156 offset:8768
	s_waitcnt lgkmcnt(1)
	v_mfma_f32_16x16x32_bf16 v[166:169], v[174:177], v[80:83], v[166:169]
	ds_read_b128 v[174:177], v156 offset:8832
	s_waitcnt lgkmcnt(1)
	v_mfma_f32_16x16x32_bf16 v[166:169], v[170:173], v[84:87], v[166:169]
	ds_read_b128 v[170:173], v156 offset:8896
	s_waitcnt lgkmcnt(1)
	v_mfma_f32_16x16x32_bf16 v[166:169], v[174:177], v[88:91], v[166:169]
	s_waitcnt lgkmcnt(0)
	v_mfma_f32_16x16x32_bf16 v[170:173], v[170:173], v[92:95], v[166:169]
	s_nop 5
	v_mul_f32_e32 v169, 0x3db8aa3b, v162
	v_mul_f32_e32 v168, 0x3db8aa3b, v163
	v_max3_f32 v155, v169, s23, v168
	v_mul_f32_e32 v167, 0x3db8aa3b, v164
	v_mul_f32_e32 v166, 0x3db8aa3b, v165
	v_max3_f32 v155, v155, v167, v166
	v_mul_f32_e32 v165, 0x3db8aa3b, v170
	v_mul_f32_e32 v163, 0x3db8aa3b, v171
	v_max3_f32 v155, v155, v165, v163
	v_mul_f32_e32 v164, 0x3db8aa3b, v172
	v_mul_f32_e32 v162, 0x3db8aa3b, v173
	v_max3_f32 v170, v155, v164, v162
	ds_bpermute_b32 v171, v154, v170
	v_cndmask_b32_e32 v155, v148, v151, vcc
	v_lshlrev_b32_e32 v155, 2, v155
	s_waitcnt lgkmcnt(0)
	v_max_f32_e32 v171, v171, v171
	v_max_f32_e32 v170, v170, v171
	ds_bpermute_b32 v171, v155, v170
	s_waitcnt lgkmcnt(0)
	v_max3_f32 v170, v161, v170, v171
	v_cmp_gt_f32_e32 vcc, v170, v161
	s_cbranch_vccz .LBB0_326
	v_sub_f32_e32 v161, v161, v170
	v_exp_f32_e32 v172, v161
	v_mov_b32_e32 v161, v170
	v_pk_mul_f32 v[62:63], v[62:63], v[172:173] op_sel_hi:[1,0]
	v_pk_mul_f32 v[60:61], v[60:61], v[172:173] op_sel_hi:[1,0]
	v_pk_mul_f32 v[58:59], v[58:59], v[172:173] op_sel_hi:[1,0]
	v_pk_mul_f32 v[56:57], v[56:57], v[172:173] op_sel_hi:[1,0]
	v_pk_mul_f32 v[54:55], v[54:55], v[172:173] op_sel_hi:[1,0]
	v_pk_mul_f32 v[52:53], v[52:53], v[172:173] op_sel_hi:[1,0]
	v_pk_mul_f32 v[50:51], v[50:51], v[172:173] op_sel_hi:[1,0]
	v_pk_mul_f32 v[48:49], v[48:49], v[172:173] op_sel_hi:[1,0]
	v_pk_mul_f32 v[46:47], v[46:47], v[172:173] op_sel_hi:[1,0]
	v_pk_mul_f32 v[44:45], v[44:45], v[172:173] op_sel_hi:[1,0]
	v_pk_mul_f32 v[42:43], v[42:43], v[172:173] op_sel_hi:[1,0]
	v_pk_mul_f32 v[40:41], v[40:41], v[172:173] op_sel_hi:[1,0]
	v_pk_mul_f32 v[38:39], v[38:39], v[172:173] op_sel_hi:[1,0]
	v_pk_mul_f32 v[36:37], v[36:37], v[172:173] op_sel_hi:[1,0]
	v_pk_mul_f32 v[34:35], v[34:35], v[172:173] op_sel_hi:[1,0]
	v_pk_mul_f32 v[32:33], v[32:33], v[172:173] op_sel_hi:[1,0]
	v_pk_mul_f32 v[30:31], v[30:31], v[172:173] op_sel_hi:[1,0]
	v_pk_mul_f32 v[28:29], v[28:29], v[172:173] op_sel_hi:[1,0]
	v_pk_mul_f32 v[26:27], v[26:27], v[172:173] op_sel_hi:[1,0]
	v_pk_mul_f32 v[24:25], v[24:25], v[172:173] op_sel_hi:[1,0]
	v_pk_mul_f32 v[22:23], v[22:23], v[172:173] op_sel_hi:[1,0]
	v_pk_mul_f32 v[20:21], v[20:21], v[172:173] op_sel_hi:[1,0]
	v_pk_mul_f32 v[18:19], v[18:19], v[172:173] op_sel_hi:[1,0]
	v_pk_mul_f32 v[16:17], v[16:17], v[172:173] op_sel_hi:[1,0]
	v_pk_mul_f32 v[14:15], v[14:15], v[172:173] op_sel_hi:[1,0]
	v_pk_mul_f32 v[12:13], v[12:13], v[172:173] op_sel_hi:[1,0]
	v_pk_mul_f32 v[10:11], v[10:11], v[172:173] op_sel_hi:[1,0]
	v_pk_mul_f32 v[8:9], v[8:9], v[172:173] op_sel_hi:[1,0]
	v_pk_mul_f32 v[6:7], v[6:7], v[172:173] op_sel_hi:[1,0]
	v_pk_mul_f32 v[4:5], v[4:5], v[172:173] op_sel_hi:[1,0]
	v_pk_mul_f32 v[2:3], v[2:3], v[172:173] op_sel_hi:[1,0]
	v_pk_mul_f32 v[0:1], v[0:1], v[172:173] op_sel_hi:[1,0]
	v_mul_f32_e32 v128, v128, v172
	s_branch .LBB0_326

; __device__ __forceinline__ unsigned cvtpk(float lo, float hi) { f32x2_t v = {lo, hi}; bf16x2_t b = __builtin_convertvector(v, bf16x2_t); return __builtin_bit_cast(unsigned, b); }
; template <int DH, int KT, int NQT, bool PF, class Ctx>
; __device__ __forceinline__ void attn_item(unsigned char* smem, const Ctx& c) {
;     ...
;           float psum = 0.f;
; #pragma unroll
;           for (int k4 = 0; k4 < NK4; ++k4)
; #pragma unroll
;             for (int j = 0; j < 4; ++j) { const float pv = __builtin_amdgcn_exp2f(s[q][k4][j] - mnew); s[q][k4][j] = pv; psum += pv; }
;           lrow[qt] += psum;
; #pragma unroll
;           for (int kk = 0; kk < NKK; ++kk) {
;             u32x4 w;
;             w.x = cvtpk(s[q][2 * kk][0], s[q][2 * kk][1]); w.y = cvtpk(s[q][2 * kk][2], s[q][2 * kk][3]);
;             w.z = cvtpk(s[q][2 * kk + 1][0], s[q][2 * kk + 1][1]); w.w = cvtpk(s[q][2 * kk + 1][2], s[q][2 * kk + 1][3]);
;             pfa[qt][kk] = __builtin_bit_cast(bf16x8, w);
;           }
;         }
;       }
; #pragma unroll
;       for (int kk = 0; kk < NKK; ++kk) {
;         const bf16_t* vb = sV + (32 * kk + 4 * quad + (l15 >> 2)) * LDK + 4 * (l15 & 3);
; #pragma unroll
;         for (int dt = 0; dt < NDT; ++dt) {
;           const s16x4 lo = tr_read(vb + 16 * dt);
;           const s16x4 hi = tr_read(vb + 16 * LDK + 16 * dt);
;           const bf16x8 vf = (bf16x8){lo[0], lo[1], lo[2], lo[3], hi[0], hi[1], hi[2], hi[3]};
; #pragma unroll
;           for (int qt = 0; qt < NQT; ++qt) o[qt][dt] = __builtin_amdgcn_mfma_f32_16x16x32_bf16(vf, pfa[qt][kk], o[qt][dt], 0, 0, 0);
;         }
;       }
.LBB0_506:
	s_setprio 0
	v_sub_f32_e32 v112, 0xf149f2ca, v229
	v_exp_f32_e32 v112, v112
	v_sub_f32_e32 v116, v126, v229
	v_sub_f32_e32 v113, v124, v229
	v_exp_f32_e32 v117, v116
	v_sub_f32_e32 v116, v127, v229
	v_sub_f32_e32 v114, v125, v229
	v_exp_f32_e32 v113, v113
	v_add_f32_e32 v115, 0, v112
	v_exp_f32_e32 v119, v116
	v_sub_f32_e32 v116, v128, v229
	v_add_f32_e32 v115, v112, v115
	v_exp_f32_e32 v114, v114
	v_exp_f32_e32 v124, v116
	v_sub_f32_e32 v116, v129, v229
	v_add_f32_e32 v115, v112, v115
	v_exp_f32_e32 v125, v116
	v_sub_f32_e32 v116, v130, v229
	v_add_f32_e32 v115, v112, v115
	v_exp_f32_e32 v126, v116
	v_sub_f32_e32 v116, v228, v229
	v_add_f32_e32 v115, v113, v115
	v_exp_f32_e32 v127, v116
	v_sub_f32_e32 v116, v225, v229
	v_add_f32_e32 v115, v114, v115
	v_exp_f32_e32 v128, v116
	v_sub_f32_e32 v116, v224, v229
	v_add_f32_e32 v115, v117, v115
	v_exp_f32_e32 v129, v116
	v_sub_f32_e32 v116, v222, v229
	v_add_f32_e32 v115, v119, v115
	v_exp_f32_e32 v130, v116
	v_sub_f32_e32 v116, v220, v229
	v_add_f32_e32 v115, v124, v115
	v_exp_f32_e32 v207, v116
	v_cvt_pk_bf16_f32 v116, v112, v112
	v_cvt_pk_bf16_f32 v112, v124, v125
	v_sub_f32_e32 v124, v136, v217
	v_add_f32_e32 v115, v125, v115
	v_exp_f32_e32 v124, v124
	v_sub_f32_e32 v125, v137, v217
	v_add_f32_e32 v115, v126, v115
	v_cvt_pk_bf16_f32 v118, v113, v114
	v_cvt_pk_bf16_f32 v113, v126, v127
	v_exp_f32_e32 v125, v125
	v_sub_f32_e32 v126, v138, v217
	v_add_f32_e32 v115, v127, v115
	v_exp_f32_e32 v126, v126
	v_sub_f32_e32 v127, v139, v217
	v_exp_f32_e32 v127, v127
	v_add_f32_e32 v115, v128, v115
	v_cvt_pk_bf16_f32 v114, v128, v129
	v_add_f32_e32 v128, 0, v124
	v_add_f32_e32 v115, v129, v115
	v_add_f32_e32 v128, v125, v128
	v_add_f32_e32 v115, v130, v115
	v_add_f32_e32 v128, v126, v128
	v_add_f32_e32 v115, v207, v115
	v_add_f32_e32 v128, v127, v128
	v_sub_f32_e32 v129, v215, v217
	v_cvt_pk_bf16_f32 v124, v124, v125
	v_cvt_pk_bf16_f32 v125, v126, v127
	v_sub_f32_e32 v127, v199, v198
	v_add_f32_e32 v166, v115, v166
	v_cvt_pk_bf16_f32 v115, v130, v207
	v_exp_f32_e32 v129, v129
	v_sub_f32_e32 v130, v216, v217
	v_exp_f32_e32 v216, v127
	v_sub_f32_e32 v127, v200, v198
	v_exp_f32_e32 v130, v130
	v_sub_f32_e32 v134, v134, v217
	v_exp_f32_e32 v230, v127
	v_sub_f32_e32 v127, v201, v198
	v_exp_f32_e32 v134, v134
	v_sub_f32_e32 v136, v218, v217
	v_exp_f32_e32 v231, v127
	v_sub_f32_e32 v127, v202, v198
	v_exp_f32_e32 v214, v136
	v_exp_f32_e32 v232, v127
	v_sub_f32_e32 v127, v203, v198
	v_add_f32_e32 v128, v129, v128
	v_exp_f32_e32 v233, v127
	v_sub_f32_e32 v127, v204, v198
	v_add_f32_e32 v128, v130, v128
	v_exp_f32_e32 v234, v127
	v_sub_f32_e32 v127, v205, v198
	v_add_f32_e32 v128, v134, v128
	v_cvt_pk_bf16_f32 v126, v129, v130
	v_exp_f32_e32 v235, v127
	v_sub_f32_e32 v127, v206, v198
	v_sub_f32_e32 v129, 0xf149f2ca, v122
	v_add_f32_e32 v128, v214, v128
	v_exp_f32_e32 v236, v127
	v_add_u32_e32 v237, v169, v170
	v_cvt_pk_bf16_f32 v127, v134, v214
	v_exp_f32_e32 v214, v129
	v_sub_f32_e32 v136, v219, v217
	ds_read_b64_tr_b16 v[202:203], v237 offset:11520
	ds_read_b64_tr_b16 v[200:201], v237 offset:9216
	v_exp_f32_e32 v215, v136
	v_sub_f32_e32 v129, v132, v217
	v_exp_f32_e32 v129, v129
	v_sub_f32_e32 v130, v133, v217
	v_cvt_pk_bf16_f32 v226, v214, v214
	v_exp_f32_e32 v130, v130
	v_sub_f32_e32 v132, v135, v217
	v_cvt_pk_bf16_f32 v119, v117, v119
	v_mov_b32_e32 v117, v116
	v_cvt_pk_bf16_f32 v136, v216, v230
	v_cvt_pk_bf16_f32 v137, v231, v232
	v_cvt_pk_bf16_f32 v138, v233, v234
	v_cvt_pk_bf16_f32 v139, v235, v236
	v_mov_b32_e32 v227, v226
	v_mov_b32_e32 v228, v226
	v_mov_b32_e32 v229, v226
	v_exp_f32_e32 v133, v132
	v_sub_f32_e32 v132, 0xf149f2ca, v217
	s_waitcnt lgkmcnt(0)
	v_mfma_f32_16x16x32_bf16 v[60:63], v[200:203], v[136:139], v[60:63]
	v_add_f32_e32 v128, v215, v128
	v_add_f32_e32 v128, v129, v128
	v_add_f32_e32 v128, v130, v128
	v_mfma_f32_16x16x32_bf16 v[44:47], v[200:203], v[124:127], v[44:47]
	v_add_f32_e32 v128, v133, v128
	ds_read_b64_tr_b16 v[204:205], v237 offset:9248
	ds_read_b64_tr_b16 v[218:219], v237 offset:9280
	ds_read_b64_tr_b16 v[222:223], v237 offset:9312
	ds_read_b64_tr_b16 v[206:207], v237 offset:11552
	ds_read_b64_tr_b16 v[220:221], v237 offset:11584
	ds_read_b64_tr_b16 v[224:225], v237 offset:11616
	v_sub_f32_e32 v120, v120, v122
	v_mfma_f32_16x16x32_bf16 v[32:35], v[200:203], v[116:119], v[32:35]
	v_sub_f32_e32 v123, v123, v122
	v_cvt_pk_bf16_f32 v133, v130, v133
	v_mfma_f32_16x16x32_bf16 v[12:15], v[200:203], v[226:229], v[12:15]
	v_exp_f32_e32 v202, v132
	v_cvt_pk_bf16_f32 v132, v215, v129
	v_add_f32_e32 v128, v202, v128
	v_add_f32_e32 v128, v202, v128
	v_add_f32_e32 v203, v202, v128
	v_sub_f32_e32 v128, 0xf149f2ca, v198
	s_waitcnt lgkmcnt(2)
	v_mfma_f32_16x16x32_bf16 v[56:59], v[204:207], v[136:139], v[56:59]
	v_cvt_pk_bf16_f32 v134, v202, v202
	v_mov_b32_e32 v135, v134
	v_mfma_f32_16x16x32_bf16 v[40:43], v[204:207], v[124:127], v[40:43]
	v_mfma_f32_16x16x32_bf16 v[28:31], v[204:207], v[116:119], v[28:31]
	v_mfma_f32_16x16x32_bf16 v[8:11], v[204:207], v[226:229], v[8:11]
	v_exp_f32_e32 v204, v128
	v_sub_f32_e32 v128, v212, v122
	v_exp_f32_e32 v205, v128
	v_sub_f32_e32 v128, v213, v122
	v_exp_f32_e32 v206, v128
	v_sub_f32_e32 v128, v131, v122
	s_waitcnt lgkmcnt(1)
	v_mfma_f32_16x16x32_bf16 v[36:39], v[218:221], v[124:127], v[36:39]
	v_exp_f32_e32 v207, v128
	v_sub_f32_e32 v128, v208, v122
	v_exp_f32_e32 v213, v120
	s_waitcnt lgkmcnt(0)
; __device__ __forceinline__ unsigned cvtpk(float lo, float hi) { f32x2_t v = {lo, hi}; bf16x2_t b = __builtin_convertvector(v, bf16x2_t); return __builtin_bit_cast(unsigned, b); }
; template <int DH, int KT, int NQT, bool PF, class Ctx>
; __device__ __forceinline__ void attn_item(unsigned char* smem, const Ctx& c) {
;     ...
;           float psum = 0.f;
; #pragma unroll
;           for (int k4 = 0; k4 < NK4; ++k4)
; #pragma unroll
;             for (int j = 0; j < 4; ++j) { const float pv = __builtin_amdgcn_exp2f(s[q][k4][j] - mnew); s[q][k4][j] = pv; psum += pv; }
;           lrow[qt] += psum;
; #pragma unroll
;           for (int kk = 0; kk < NKK; ++kk) {
;             u32x4 w;
;             w.x = cvtpk(s[q][2 * kk][0], s[q][2 * kk][1]); w.y = cvtpk(s[q][2 * kk][2], s[q][2 * kk][3]);
;             w.z = cvtpk(s[q][2 * kk + 1][0], s[q][2 * kk + 1][1]); w.w = cvtpk(s[q][2 * kk + 1][2], s[q][2 * kk + 1][3]);
;             pfa[qt][kk] = __builtin_bit_cast(bf16x8, w);
;           }
;         }
;       }
; #pragma unroll
;       for (int kk = 0; kk < NKK; ++kk) {
;         const bf16_t* vb = sV + (32 * kk + 4 * quad + (l15 >> 2)) * LDK + 4 * (l15 & 3);
; #pragma unroll
;         for (int dt = 0; dt < NDT; ++dt) {
;           const s16x4 lo = tr_read(vb + 16 * dt);
;           const s16x4 hi = tr_read(vb + 16 * LDK + 16 * dt);
;           const bf16x8 vf = (bf16x8){lo[0], lo[1], lo[2], lo[3], hi[0], hi[1], hi[2], hi[3]};
; #pragma unroll
;           for (int qt = 0; qt < NQT; ++qt) o[qt][dt] = __builtin_amdgcn_mfma_f32_16x16x32_bf16(vf, pfa[qt][kk], o[qt][dt], 0, 0, 0);
;         }
;       }
	v_mfma_f32_16x16x32_bf16 v[24:27], v[222:225], v[124:127], v[24:27]
	v_sub_f32_e32 v124, v209, v122
	v_sub_f32_e32 v120, v121, v122
	v_exp_f32_e32 v208, v128
	v_mfma_f32_16x16x32_bf16 v[20:23], v[218:221], v[116:119], v[20:23]
	v_exp_f32_e32 v209, v124
	v_exp_f32_e32 v212, v123
	v_exp_f32_e32 v215, v120
	v_mfma_f32_16x16x32_bf16 v[16:19], v[222:225], v[116:119], v[16:19]
	ds_read_b64_tr_b16 v[116:117], v237 offset:13824
	ds_read_b64_tr_b16 v[118:119], v237 offset:16128
	v_cvt_pk_bf16_f32 v198, v204, v204
	v_mov_b32_e32 v199, v198
	v_mov_b32_e32 v200, v198
	v_mov_b32_e32 v201, v198
	v_cvt_pk_bf16_f32 v120, v205, v206
	v_cvt_pk_bf16_f32 v121, v207, v208
	v_cvt_pk_bf16_f32 v122, v209, v212
	v_cvt_pk_bf16_f32 v123, v213, v215
	s_waitcnt lgkmcnt(0)
	v_mfma_f32_16x16x32_bf16 v[60:63], v[116:119], v[198:201], v[60:63]
	v_mfma_f32_16x16x32_bf16 v[44:47], v[116:119], v[132:135], v[44:47]
	v_mfma_f32_16x16x32_bf16 v[32:35], v[116:119], v[112:115], v[32:35]
	v_mfma_f32_16x16x32_bf16 v[12:15], v[116:119], v[120:123], v[12:15]
	v_add_f32_e32 v116, v202, v203
	v_add_f32_e32 v167, v116, v167
	v_add_f32_e32 v116, 0, v216
	v_add_f32_e32 v116, v230, v116
	v_add_f32_e32 v116, v231, v116
	v_add_f32_e32 v116, v232, v116
	v_add_f32_e32 v116, v233, v116
	v_add_f32_e32 v116, v234, v116
	v_add_f32_e32 v116, v235, v116
	v_add_f32_e32 v116, v236, v116
	v_add_f32_e32 v116, v204, v116
	v_add_f32_e32 v116, v204, v116
	v_add_f32_e32 v116, v204, v116
	v_add_f32_e32 v116, v204, v116
	v_add_f32_e32 v116, v204, v116
	v_add_f32_e32 v116, v204, v116
	v_add_f32_e32 v116, v204, v116
	v_add_f32_e32 v116, v204, v116
	v_add_f32_e32 v168, v116, v168
	v_add_f32_e32 v116, 0, v214
	v_add_f32_e32 v116, v214, v116
	v_add_f32_e32 v116, v214, v116
	v_add_f32_e32 v116, v214, v116
	v_add_f32_e32 v116, v214, v116
	v_add_f32_e32 v116, v214, v116
	v_add_f32_e32 v116, v214, v116
	v_add_f32_e32 v116, v214, v116
	v_mfma_f32_16x16x32_bf16 v[52:55], v[218:221], v[136:139], v[52:55]
	v_add_f32_e32 v116, v205, v116
	v_add_f32_e32 v116, v206, v116
	v_add_f32_e32 v116, v207, v116
	v_mfma_f32_16x16x32_bf16 v[48:51], v[222:225], v[136:139], v[48:51]
	ds_read_b64_tr_b16 v[124:125], v237 offset:13856
	ds_read_b64_tr_b16 v[128:129], v237 offset:13888
	ds_read_b64_tr_b16 v[136:137], v237 offset:13920
	ds_read_b64_tr_b16 v[126:127], v237 offset:16160
	ds_read_b64_tr_b16 v[130:131], v237 offset:16192
	ds_read_b64_tr_b16 v[138:139], v237 offset:16224
	v_add_f32_e32 v116, v208, v116
	v_add_f32_e32 v116, v209, v116
	v_mfma_f32_16x16x32_bf16 v[4:7], v[218:221], v[226:229], v[4:7]
	v_add_f32_e32 v116, v212, v116
	v_mfma_f32_16x16x32_bf16 v[0:3], v[222:225], v[226:229], v[0:3]
	s_waitcnt lgkmcnt(2)
	v_mfma_f32_16x16x32_bf16 v[56:59], v[124:127], v[198:201], v[56:59]
	v_mfma_f32_16x16x32_bf16 v[40:43], v[124:127], v[132:135], v[40:43]
	v_mfma_f32_16x16x32_bf16 v[28:31], v[124:127], v[112:115], v[28:31]
	v_mfma_f32_16x16x32_bf16 v[8:11], v[124:127], v[120:123], v[8:11]
	s_waitcnt lgkmcnt(1)
	v_mfma_f32_16x16x32_bf16 v[52:55], v[128:131], v[198:201], v[52:55]
	v_mfma_f32_16x16x32_bf16 v[36:39], v[128:131], v[132:135], v[36:39]
	v_mfma_f32_16x16x32_bf16 v[20:23], v[128:131], v[112:115], v[20:23]
	v_mfma_f32_16x16x32_bf16 v[4:7], v[128:131], v[120:123], v[4:7]
	s_waitcnt lgkmcnt(0)
	v_mfma_f32_16x16x32_bf16 v[48:51], v[136:139], v[198:201], v[48:51]
	v_mfma_f32_16x16x32_bf16 v[24:27], v[136:139], v[132:135], v[24:27]
	v_mfma_f32_16x16x32_bf16 v[16:19], v[136:139], v[112:115], v[16:19]
	v_add_f32_e32 v112, v213, v116
	v_add_f32_e32 v112, v215, v112
	v_add_f32_e32 v165, v112, v165
	v_mfma_f32_16x16x32_bf16 v[0:3], v[136:139], v[120:123], v[0:3]
.LBB0_507:
	s_setprio 0
	s_add_i32 s8, s8, 31
	s_cmpk_lg_i32 s8, 0x136
	s_cbranch_scc0 .LBB0_517
; __device__ __forceinline__ void ld16_sc1(u32x4& v, const void* p) { asm volatile("global_load_dwordx4 %0, %1, off sc1" : "=v"(v) : "v"(p) : "memory"); }
; template <int DH, int KT, int NQT, bool PF, class Ctx>
; __device__ __forceinline__ void attn_item(unsigned char* smem, const Ctx& c) {
;     ...
;     __syncthreads();
;     if constexpr (PF) {
;       static_assert(!PF || NCH == 2 || NCH == 4, "wait lists below are written for two or four chunks per matrix");
;       if constexpr (NCH == 2) asm volatile("s_waitcnt vmcnt(0)" : "+v"(rk[0]), "+v"(rk[NCH - 1]), "+v"(rv[0]), "+v"(rv[NCH - 1]) :: "memory");
;       else asm volatile("s_waitcnt vmcnt(0)" : "+v"(rk[0]), "+v"(rk[1]), "+v"(rk[NCH - 2]), "+v"(rk[NCH - 1]), "+v"(rv[0]), "+v"(rv[1]), "+v"(rv[NCH - 2]), "+v"(rv[NCH - 1]) :: "memory");
; #pragma unroll
;       for (int i = 0; i < NCH; ++i) {
;         const int ci = tid + 256 * i, row = ci / CH, ch = ci % CH;
;         *(u32x4*)(sK + row * LDK + ch * 8) = rk[i]; *(u32x4*)(sV + row * LDK + ch * 8) = rv[i];
;       }
;     } else {
; #pragma unroll
;       for (int i = 0; i < NCH; ++i) {
;         const int ci = tid + 256 * i, row = ci / CH, ch = ci % CH;
;         *(u32x4*)(sK + row * LDK + ch * 8) = ld_agent_u32x4(c.kptr(t, row) + ch * 8);
;       }
; #pragma unroll
;       for (int i = 0; i < NCH; ++i) {
;         const int ci = tid + 256 * i, row = ci / CH, ch = ci % CH;
;         *(u32x4*)(sV + row * LDK + ch * 8) = ld_agent_u32x4(c.vptr(t, row) + ch * 8);
;       }
;     }
;     __syncthreads();
;     if constexpr (PF) {
;       if (t + 1 < nt) {
; #pragma unroll
;         for (int i = 0; i < NCH; ++i) {
;           const int ci = tid + 256 * i, row = ci / CH, ch = ci % CH;
;           ld16_sc1(rk[i], c.kptr(t + 1, row) + ch * 8); ld16_sc1(rv[i], c.vptr(t + 1, row) + ch * 8);
;         }
;     ...
;         for (int k4 = 0; k4 < NK4; ++k4)
; #pragma unroll
;           for (int ks = 0; ks < NKS; ++ks) {
;             const bf16x8 kf = *(const bf16x8*)(sK + (16 * k4 + l15) * LDK + ks * 32 + quad * 8);
; #pragma unroll
;             for (int q = 0; q < QG; ++q) s[q][k4] = __builtin_amdgcn_mfma_f32_16x16x32_bf16(kf, qf[g + q][ks], s[q][k4], 0, 0, 0);
;           }
; #pragma unroll
;         for (int q = 0; q < QG; ++q) {
;           const int qt = g + q;
;           float mx = -1e30f;
; #pragma unroll
;           for (int k4 = 0; k4 < NK4; ++k4)
; #pragma unroll
.LBB0_508:
	s_setprio 1
	s_barrier
	s_waitcnt vmcnt(0)
	s_mov_b32 s2, s33
	s_add_i32 s33, s33, 1
	s_min_i32 s3, s33, s0
	s_lshl_b32 s3, s3, 6
	ds_write_b128 v195, v[96:99]
	ds_write_b128 v195, v[100:103] offset:9216
	ds_write_b128 v196, v[104:107]
	ds_write_b128 v196, v[108:111] offset:9216
	v_add_u32_e32 v96, s3, v193
	v_mov_b64_e32 v[104:105], s[10:11]
	v_mad_i64_i32 v[96:97], vcc, v96, s12, v[104:105]
	v_lshl_add_u64 v[96:97], v[96:97], 0, s[14:15]
	v_add_u32_e32 v106, s3, v194
	v_lshl_add_u64 v[100:101], v[154:155], 1, v[96:97]
	v_mad_i64_i32 v[104:105], vcc, v106, s12, v[104:105]
	v_lshl_add_u64 v[96:97], v[100:101], 0, s[16:17]
	v_lshl_add_u64 v[104:105], v[104:105], 0, s[14:15]
	s_waitcnt lgkmcnt(0)
	s_barrier
	global_load_dwordx4 v[96:99], v[96:97], off sc1
	v_lshl_add_u64 v[100:101], v[100:101], 0, s[4:5]
	v_lshl_add_u64 v[108:109], v[156:157], 1, v[104:105]
	global_load_dwordx4 v[100:103], v[100:101], off sc1
	v_lshl_add_u64 v[104:105], v[108:109], 0, s[16:17]
	s_cmp_ge_u32 s2, s1
	global_load_dwordx4 v[104:107], v[104:105], off sc1
	v_lshl_add_u64 v[108:109], v[108:109], 0, s[4:5]
	s_cselect_b64 vcc, -1, 0
	s_cmp_lt_u32 s2, s9
	s_cselect_b64 s[2:3], -1, 0
	global_load_dwordx4 v[108:111], v[108:109], off sc1
	s_and_b64 s[2:3], vcc, s[2:3]
	s_andn2_b64 vcc, exec, s[2:3]
	s_cbranch_vccnz .LBB0_507
	v_add_u32_e32 v228, v142, v192
	ds_read_b128 v[112:115], v228
	ds_read_b128 v[116:119], v228 offset:64
	v_and_b32_e32 v128, 64, v163
	v_xor_b32_e32 v132, 16, v163
	v_add_u32_e32 v214, 64, v128
	s_waitcnt lgkmcnt(1)
	v_mfma_f32_16x16x32_bf16 v[120:123], v[112:115], v[92:95], 0
	v_cmp_lt_i32_e32 vcc, v132, v214
	v_add_u32_e32 v215, s8, v197
	v_add_u32_e32 v208, 0xe8, v215
	s_nop 0
	v_mfma_f32_16x16x32_bf16 v[124:127], v[112:115], v[80:83], 0
	ds_read_b128 v[112:115], v228 offset:2304
	v_add_u32_e32 v209, 0xe9, v215
	v_add_u32_e32 v212, 0xea, v215
	s_waitcnt lgkmcnt(1)
	v_mfma_f32_16x16x32_bf16 v[128:131], v[116:119], v[88:91], v[120:123]
	v_add_u32_e32 v213, 0xeb, v215
	v_add_u32_e32 v225, 0xf8, v215
	v_add_u32_e32 v224, 0xf9, v215
	v_cndmask_b32_e32 v120, v163, v132, vcc
	v_lshlrev_b32_e32 v207, 2, v120
	s_nop 0
	v_mfma_f32_16x16x32_bf16 v[136:139], v[116:119], v[84:87], v[124:127]
	ds_read_b128 v[116:119], v228 offset:2368
	ds_read_b128 v[120:123], v228 offset:4608
	v_add_u32_e32 v222, 0xfa, v215
	v_add_u32_e32 v220, 0xfb, v215
	s_waitcnt lgkmcnt(2)
	v_mfma_f32_16x16x32_bf16 v[124:127], v[112:115], v[92:95], 0
	v_cndmask_b32_e64 v132, v208, 0, s[6:7]
	v_cndmask_b32_e64 v200, v209, 0, s[96:97]
	v_cndmask_b32_e64 v201, v212, 0, s[94:95]
	v_cndmask_b32_e64 v202, v213, 0, s[92:93]
	v_cndmask_b32_e64 v203, 0, v225, s[90:91]
	v_cndmask_b32_e64 v204, 0, v224, s[88:89]
	v_cndmask_b32_e64 v205, 0, v222, s[86:87]
	v_cndmask_b32_e64 v206, 0, v220, s[84:85]
	v_lshlrev_b32_e32 v199, 2, v132
	v_lshlrev_b32_e32 v200, 2, v200
	s_waitcnt lgkmcnt(1)
	v_mfma_f32_16x16x32_bf16 v[124:127], v[116:119], v[88:91], v[124:127]
	v_lshlrev_b32_e32 v201, 2, v201
	v_lshlrev_b32_e32 v202, 2, v202
	v_lshlrev_b32_e32 v203, 2, v203
	v_lshlrev_b32_e32 v204, 2, v204
	v_lshlrev_b32_e32 v205, 2, v205
	v_lshlrev_b32_e32 v206, 2, v206
	ds_read_b32 v199, v199 offset:18432
	ds_read_b32 v200, v200 offset:18432
	ds_read_b32 v201, v201 offset:18432
	ds_read_b32 v202, v202 offset:18432
	ds_read_b32 v203, v203 offset:18432
	ds_read_b32 v204, v204 offset:18432
	ds_read_b32 v205, v205 offset:18432
	ds_read_b32 v206, v206 offset:18432
	s_waitcnt lgkmcnt(7)
	v_fmac_f32_e32 v199, 0x3e000000, v128
	s_waitcnt lgkmcnt(6)
	v_fmac_f32_e32 v200, 0x3e000000, v129
	v_mul_f32_e32 v128, 0x3fb8aa3b, v199
	v_mul_f32_e32 v129, 0x3fb8aa3b, v200
	s_waitcnt lgkmcnt(5)
	v_fmac_f32_e32 v201, 0x3e000000, v130
	v_cndmask_b32_e64 v199, v128, v164, s[6:7]
	v_cndmask_b32_e64 v200, v129, v164, s[96:97]
	v_mul_f32_e32 v129, 0x3fb8aa3b, v201
	s_waitcnt lgkmcnt(4)
	v_fmac_f32_e32 v202, 0x3e000000, v131
	s_waitcnt lgkmcnt(3)
	v_fmac_f32_e32 v203, 0x3e000000, v124
	s_waitcnt lgkmcnt(2)
	v_fmac_f32_e32 v204, 0x3e000000, v125
	v_max_f32_e32 v128, 0xf149f2ca, v199
	v_cndmask_b32_e64 v201, v129, v164, s[94:95]
	v_mul_f32_e32 v129, 0x3fb8aa3b, v202
	v_mul_f32_e32 v124, 0x3fb8aa3b, v203
	v_mul_f32_e32 v125, 0x3fb8aa3b, v204
	s_waitcnt lgkmcnt(1)
	v_fmac_f32_e32 v205, 0x3e000000, v126
	v_max3_f32 v128, v128, v200, v201
	v_cndmask_b32_e64 v202, v129, v164, s[92:93]
	v_cndmask_b32_e64 v203, v164, v124, s[90:91]
	v_cndmask_b32_e64 v204, v164, v125, s[88:89]
	v_mul_f32_e32 v125, 0x3fb8aa3b, v205
	s_waitcnt lgkmcnt(0)
	v_fmac_f32_e32 v206, 0x3e000000, v127
	v_max3_f32 v124, v128, v202, v203
	v_cndmask_b32_e64 v205, v164, v125, s[86:87]
	v_mul_f32_e32 v125, 0x3fb8aa3b, v206
	v_max3_f32 v124, v124, v204, v205
	v_cndmask_b32_e64 v206, v164, v125, s[84:85]
	v_max3_f32 v216, v124, v206, s13
	ds_bpermute_b32 v217, v207, v216
	ds_read_b128 v[124:127], v228 offset:4672
	v_xor_b32_e32 v198, 32, v163
	v_cmp_lt_i32_e32 vcc, v198, v214
	v_mfma_f32_16x16x32_bf16 v[132:135], v[112:115], v[80:83], 0
	s_nop 0
	v_cndmask_b32_e32 v128, v163, v198, vcc
	s_waitcnt lgkmcnt(1)
	v_max_f32_e32 v198, v217, v217
	v_lshlrev_b32_e32 v214, 2, v128
	v_mfma_f32_16x16x32_bf16 v[128:131], v[120:123], v[80:83], 0
	v_max_f32_e32 v198, v216, v198
	ds_bpermute_b32 v216, v214, v198
	s_waitcnt lgkmcnt(0)
	v_max3_f32 v198, v191, v198, v216
	v_mfma_f32_16x16x32_bf16 v[132:135], v[116:119], v[84:87], v[132:135]
	v_cmp_gt_f32_e32 vcc, v198, v191
	v_mfma_f32_16x16x32_bf16 v[128:131], v[124:127], v[84:87], v[128:131]
	s_cbranch_vccz .LBB0_511
	v_sub_f32_e32 v191, v191, v198
	v_exp_f32_e32 v216, v191
	v_mov_b32_e32 v191, v198
	v_mul_f32_e32 v168, v168, v216
	v_pk_mul_f32 v[62:63], v[62:63], v[216:217] op_sel_hi:[1,0]
	v_pk_mul_f32 v[60:61], v[60:61], v[216:217] op_sel_hi:[1,0]
	v_pk_mul_f32 v[58:59], v[58:59], v[216:217] op_sel_hi:[1,0]
	v_pk_mul_f32 v[56:57], v[56:57], v[216:217] op_sel_hi:[1,0]
	v_pk_mul_f32 v[54:55], v[54:55], v[216:217] op_sel_hi:[1,0]
	v_pk_mul_f32 v[52:53], v[52:53], v[216:217] op_sel_hi:[1,0]
	v_pk_mul_f32 v[50:51], v[50:51], v[216:217] op_sel_hi:[1,0]
	v_pk_mul_f32 v[48:49], v[48:49], v[216:217] op_sel_hi:[1,0]

; __device__ __forceinline__ unsigned cvtpk(float lo, float hi) { f32x2_t v = {lo, hi}; bf16x2_t b = __builtin_convertvector(v, bf16x2_t); return __builtin_bit_cast(unsigned, b); }
; template <int DH, int KT, int NQT, bool PF, class Ctx>
; __device__ __forceinline__ void attn_item(unsigned char* smem, const Ctx& c) {
;     ...
;           float psum = 0.f;
; #pragma unroll
;           for (int k4 = 0; k4 < NK4; ++k4)
; #pragma unroll
;             for (int j = 0; j < 4; ++j) { const float pv = __builtin_amdgcn_exp2f(s[q][k4][j] - mnew); s[q][k4][j] = pv; psum += pv; }
;           lrow[qt] += psum;
; #pragma unroll
;           for (int kk = 0; kk < NKK; ++kk) {
;             u32x4 w;
;             w.x = cvtpk(s[q][2 * kk][0], s[q][2 * kk][1]); w.y = cvtpk(s[q][2 * kk][2], s[q][2 * kk][3]);
;             w.z = cvtpk(s[q][2 * kk + 1][0], s[q][2 * kk + 1][1]); w.w = cvtpk(s[q][2 * kk + 1][2], s[q][2 * kk + 1][3]);
;             pfa[qt][kk] = __builtin_bit_cast(bf16x8, w);
;           }
;         }
;       }
; #pragma unroll
;       for (int kk = 0; kk < NKK; ++kk) {
;         const bf16_t* vb = sV + (32 * kk + 4 * quad + (l15 >> 2)) * LDK + 4 * (l15 & 3);
; #pragma unroll
;         for (int dt = 0; dt < NDT; ++dt) {
;           const s16x4 lo = tr_read(vb + 16 * dt);
;           const s16x4 hi = tr_read(vb + 16 * LDK + 16 * dt);
;           const bf16x8 vf = (bf16x8){lo[0], lo[1], lo[2], lo[3], hi[0], hi[1], hi[2], hi[3]};
; #pragma unroll
;           for (int qt = 0; qt < NQT; ++qt) o[qt][dt] = __builtin_amdgcn_mfma_f32_16x16x32_bf16(vf, pfa[qt][kk], o[qt][dt], 0, 0, 0);
;         }
;       }
.LBB0_616:
	s_setprio 0
	v_sub_f32_e32 v163, v163, v170
	v_sub_f32_e32 v169, v169, v170
	v_sub_f32_e32 v168, v168, v170
	v_sub_f32_e32 v167, v167, v170
	v_sub_f32_e32 v166, v166, v170
	v_sub_f32_e32 v165, v165, v170
	v_exp_f32_e32 v187, v163
	v_sub_f32_e32 v163, v164, v170
	v_sub_f32_e32 v162, v162, v170
	v_exp_f32_e32 v182, v169
	v_exp_f32_e32 v183, v168
	v_exp_f32_e32 v184, v167
	v_exp_f32_e32 v185, v166
	v_exp_f32_e32 v186, v165
	v_exp_f32_e32 v188, v163
	v_exp_f32_e32 v189, v162
	ds_read_b64_tr_b16 v[168:169], v153 offset:25344
	ds_read_b64_tr_b16 v[166:167], v153 offset:16896
	v_cvt_pk_bf16_f32 v162, v182, v183
	v_cvt_pk_bf16_f32 v163, v184, v185
	v_cvt_pk_bf16_f32 v164, v186, v187
	v_cvt_pk_bf16_f32 v165, v188, v189
	ds_read_b64_tr_b16 v[172:173], v153 offset:25376
	ds_read_b64_tr_b16 v[170:171], v153 offset:16928
	ds_read_b64_tr_b16 v[174:175], v153 offset:16960
	ds_read_b64_tr_b16 v[178:179], v153 offset:16992
	ds_read_b64_tr_b16 v[176:177], v153 offset:25408
	ds_read_b64_tr_b16 v[180:181], v153 offset:25440
	s_waitcnt lgkmcnt(6)
	v_mfma_f32_16x16x32_bf16 v[60:63], v[166:169], v[162:165], v[60:63]
	ds_read_b64_tr_b16 v[166:167], v153 offset:17024
	ds_read_b64_tr_b16 v[168:169], v153 offset:25472
	s_add_u32 s12, s12, 0x20000
	s_addc_u32 s13, s13, 0
	s_waitcnt lgkmcnt(6)
	v_mfma_f32_16x16x32_bf16 v[56:59], v[170:173], v[162:165], v[56:59]
	s_cmp_eq_u32 s12, 0xe0000
	s_waitcnt lgkmcnt(3)
	v_mfma_f32_16x16x32_bf16 v[52:55], v[174:177], v[162:165], v[52:55]
	s_waitcnt lgkmcnt(2)
	v_mfma_f32_16x16x32_bf16 v[48:51], v[178:181], v[162:165], v[48:51]
	ds_read_b64_tr_b16 v[172:173], v153 offset:25504
	ds_read_b64_tr_b16 v[170:171], v153 offset:17056
	ds_read_b64_tr_b16 v[174:175], v153 offset:17088
	ds_read_b64_tr_b16 v[178:179], v153 offset:17120
	ds_read_b64_tr_b16 v[176:177], v153 offset:25536
	ds_read_b64_tr_b16 v[180:181], v153 offset:25568
	s_waitcnt lgkmcnt(6)
	v_mfma_f32_16x16x32_bf16 v[44:47], v[166:169], v[162:165], v[44:47]
	ds_read_b64_tr_b16 v[166:167], v153 offset:17152
	ds_read_b64_tr_b16 v[168:169], v153 offset:25600
	s_waitcnt lgkmcnt(6)
	v_mfma_f32_16x16x32_bf16 v[40:43], v[170:173], v[162:165], v[40:43]
	s_waitcnt lgkmcnt(3)
	v_mfma_f32_16x16x32_bf16 v[36:39], v[174:177], v[162:165], v[36:39]
	s_waitcnt lgkmcnt(2)
	v_mfma_f32_16x16x32_bf16 v[32:35], v[178:181], v[162:165], v[32:35]
	ds_read_b64_tr_b16 v[172:173], v153 offset:25632
	ds_read_b64_tr_b16 v[170:171], v153 offset:17184
	ds_read_b64_tr_b16 v[174:175], v153 offset:17216
	ds_read_b64_tr_b16 v[178:179], v153 offset:17248
	ds_read_b64_tr_b16 v[176:177], v153 offset:25664
	ds_read_b64_tr_b16 v[180:181], v153 offset:25696
	s_waitcnt lgkmcnt(6)
	v_mfma_f32_16x16x32_bf16 v[28:31], v[166:169], v[162:165], v[28:31]
	ds_read_b64_tr_b16 v[166:167], v153 offset:17280
	ds_read_b64_tr_b16 v[168:169], v153 offset:25728
	s_waitcnt lgkmcnt(6)
	v_mfma_f32_16x16x32_bf16 v[24:27], v[170:173], v[162:165], v[24:27]
	s_waitcnt lgkmcnt(3)
	v_mfma_f32_16x16x32_bf16 v[20:23], v[174:177], v[162:165], v[20:23]
	s_waitcnt lgkmcnt(2)
	v_mfma_f32_16x16x32_bf16 v[16:19], v[178:181], v[162:165], v[16:19]
	ds_read_b64_tr_b16 v[172:173], v153 offset:25760
	ds_read_b64_tr_b16 v[170:171], v153 offset:17312
	ds_read_b64_tr_b16 v[174:175], v153 offset:17344
	ds_read_b64_tr_b16 v[178:179], v153 offset:17376
	ds_read_b64_tr_b16 v[176:177], v153 offset:25792
	ds_read_b64_tr_b16 v[180:181], v153 offset:25824
	s_waitcnt lgkmcnt(6)
	v_mfma_f32_16x16x32_bf16 v[12:15], v[166:169], v[162:165], v[12:15]
	v_add_f32_e32 v166, 0, v182
	v_add_f32_e32 v166, v183, v166
	v_add_f32_e32 v166, v184, v166
	v_add_f32_e32 v166, v185, v166
	s_waitcnt lgkmcnt(4)
	v_mfma_f32_16x16x32_bf16 v[8:11], v[170:173], v[162:165], v[8:11]
	s_waitcnt lgkmcnt(1)
	v_mfma_f32_16x16x32_bf16 v[4:7], v[174:177], v[162:165], v[4:7]
	s_waitcnt lgkmcnt(0)
	v_mfma_f32_16x16x32_bf16 v[0:3], v[178:181], v[162:165], v[0:3]
	v_add_f32_e32 v162, v186, v166
	v_add_f32_e32 v162, v187, v162
	v_add_f32_e32 v162, v188, v162
	v_add_f32_e32 v162, v189, v162
	v_add_f32_e32 v128, v162, v128
	s_cbranch_scc1 .LBB0_619
; __device__ __forceinline__ void ld16_sc1(u32x4& v, const void* p) { asm volatile("global_load_dwordx4 %0, %1, off sc1" : "=v"(v) : "v"(p) : "memory"); }
; template <int DH, int KT, int NQT, bool PF, class Ctx>
; __device__ __forceinline__ void attn_item(unsigned char* smem, const Ctx& c) {
;     ...
;     __syncthreads();
;     if constexpr (PF) {
;       static_assert(!PF || NCH == 2 || NCH == 4, "wait lists below are written for two or four chunks per matrix");
;       if constexpr (NCH == 2) asm volatile("s_waitcnt vmcnt(0)" : "+v"(rk[0]), "+v"(rk[NCH - 1]), "+v"(rv[0]), "+v"(rv[NCH - 1]) :: "memory");
;       else asm volatile("s_waitcnt vmcnt(0)" : "+v"(rk[0]), "+v"(rk[1]), "+v"(rk[NCH - 2]), "+v"(rk[NCH - 1]), "+v"(rv[0]), "+v"(rv[1]), "+v"(rv[NCH - 2]), "+v"(rv[NCH - 1]) :: "memory");
; #pragma unroll
;       for (int i = 0; i < NCH; ++i) {
;         const int ci = tid + 256 * i, row = ci / CH, ch = ci % CH;
;         *(u32x4*)(sK + row * LDK + ch * 8) = rk[i]; *(u32x4*)(sV + row * LDK + ch * 8) = rv[i];
;       }
;     } else {
; #pragma unroll
;       for (int i = 0; i < NCH; ++i) {
;         const int ci = tid + 256 * i, row = ci / CH, ch = ci % CH;
;         *(u32x4*)(sK + row * LDK + ch * 8) = ld_agent_u32x4(c.kptr(t, row) + ch * 8);
;       }
; #pragma unroll
;       for (int i = 0; i < NCH; ++i) {
;         const int ci = tid + 256 * i, row = ci / CH, ch = ci % CH;
;         *(u32x4*)(sV + row * LDK + ch * 8) = ld_agent_u32x4(c.vptr(t, row) + ch * 8);
;       }
;     }
;     __syncthreads();
;     if constexpr (PF) {
;       if (t + 1 < nt) {
; #pragma unroll
;         for (int i = 0; i < NCH; ++i) {
;           const int ci = tid + 256 * i, row = ci / CH, ch = ci % CH;
;           ld16_sc1(rk[i], c.kptr(t + 1, row) + ch * 8); ld16_sc1(rv[i], c.vptr(t + 1, row) + ch * 8);
;         }
;     ...
;         for (int k4 = 0; k4 < NK4; ++k4)
; #pragma unroll
;           for (int ks = 0; ks < NKS; ++ks) {
;             const bf16x8 kf = *(const bf16x8*)(sK + (16 * k4 + l15) * LDK + ks * 32 + quad * 8);
; #pragma unroll
;             for (int q = 0; q < QG; ++q) s[q][k4] = __builtin_amdgcn_mfma_f32_16x16x32_bf16(kf, qf[g + q][ks], s[q][k4], 0, 0, 0);
;           }
; #pragma unroll
;         for (int q = 0; q < QG; ++q) {
;           const int qt = g + q;
;           float mx = -1e30f;
; #pragma unroll
;           for (int k4 = 0; k4 < NK4; ++k4)
; #pragma unroll
.LBB0_617:
	s_setprio 1
	s_barrier
	s_waitcnt vmcnt(0)
	ds_write_b128 v157, v[96:99]
	ds_write_b128 v157, v[100:103] offset:16896
	ds_write_b128 v158, v[104:107]
	ds_write_b128 v158, v[108:111] offset:16896
	ds_write_b128 v159, v[112:115]
	ds_write_b128 v159, v[116:119] offset:16896
	ds_write_b128 v160, v[120:123]
	ds_write_b128 v160, v[124:127] offset:16896
	v_lshl_add_u64 v[96:97], v[146:147], 0, s[12:13]
	v_lshl_add_u64 v[100:101], v[132:133], 1, v[96:97]
	v_lshl_add_u64 v[96:97], v[100:101], 0, s[8:9]
	v_lshl_add_u64 v[104:105], v[144:145], 0, s[12:13]
	s_waitcnt lgkmcnt(0)
	s_barrier
	global_load_dwordx4 v[96:99], v[96:97], off sc1
	v_lshl_add_u64 v[100:101], v[100:101], 0, s[10:11]
	v_lshl_add_u64 v[108:109], v[134:135], 1, v[104:105]
	global_load_dwordx4 v[100:103], v[100:101], off sc1
	v_lshl_add_u64 v[104:105], v[108:109], 0, s[8:9]
	v_lshl_add_u64 v[112:113], v[142:143], 0, s[12:13]
	global_load_dwordx4 v[104:107], v[104:105], off sc1
	v_lshl_add_u64 v[108:109], v[108:109], 0, s[10:11]
	v_lshl_add_u64 v[116:117], v[136:137], 1, v[112:113]
	global_load_dwordx4 v[108:111], v[108:109], off sc1
	v_lshl_add_u64 v[112:113], v[116:117], 0, s[8:9]
	v_lshl_add_u64 v[120:121], v[140:141], 0, s[12:13]
	global_load_dwordx4 v[112:115], v[112:113], off sc1
	v_lshl_add_u64 v[116:117], v[116:117], 0, s[10:11]
	v_lshl_add_u64 v[124:125], v[138:139], 1, v[120:121]
	global_load_dwordx4 v[116:119], v[116:117], off sc1
	v_lshl_add_u64 v[120:121], v[124:125], 0, s[8:9]
	global_load_dwordx4 v[120:123], v[120:121], off sc1
	v_lshl_add_u64 v[124:125], v[124:125], 0, s[10:11]
	global_load_dwordx4 v[124:127], v[124:125], off sc1
	ds_read_b128 v[162:165], v156
	ds_read_b128 v[166:169], v156 offset:64
	s_waitcnt lgkmcnt(1)
	v_mfma_f32_16x16x32_bf16 v[162:165], v[162:165], v[72:75], 0
	ds_read_b128 v[170:173], v156 offset:128
	ds_read_b128 v[174:177], v156 offset:8576
	v_cmp_lt_i32_e32 vcc, v149, v150
	s_waitcnt lgkmcnt(2)
	v_mfma_f32_16x16x32_bf16 v[162:165], v[166:169], v[76:79], v[162:165]
	ds_read_b128 v[166:169], v156 offset:192
	v_cndmask_b32_e32 v154, v148, v149, vcc
	v_lshlrev_b32_e32 v154, 2, v154
	s_waitcnt lgkmcnt(2)
	v_mfma_f32_16x16x32_bf16 v[162:165], v[170:173], v[64:67], v[162:165]
	ds_read_b128 v[170:173], v156 offset:256
	v_cmp_lt_i32_e32 vcc, v151, v150
	s_waitcnt lgkmcnt(1)
	v_mfma_f32_16x16x32_bf16 v[162:165], v[166:169], v[68:71], v[162:165]
	ds_read_b128 v[166:169], v156 offset:320
	s_waitcnt lgkmcnt(1)
	v_mfma_f32_16x16x32_bf16 v[162:165], v[170:173], v[80:83], v[162:165]
	ds_read_b128 v[170:173], v156 offset:384
	s_waitcnt lgkmcnt(1)
	v_mfma_f32_16x16x32_bf16 v[162:165], v[166:169], v[84:87], v[162:165]
	ds_read_b128 v[166:169], v156 offset:448
	s_waitcnt lgkmcnt(1)
	v_mfma_f32_16x16x32_bf16 v[162:165], v[170:173], v[88:91], v[162:165]
	ds_read_b128 v[170:173], v156 offset:8448
	s_waitcnt lgkmcnt(1)
	v_mfma_f32_16x16x32_bf16 v[162:165], v[166:169], v[92:95], v[162:165]
	ds_read_b128 v[166:169], v156 offset:8512
	s_waitcnt lgkmcnt(1)
	v_mfma_f32_16x16x32_bf16 v[170:173], v[170:173], v[72:75], 0
	s_waitcnt lgkmcnt(0)
	v_mfma_f32_16x16x32_bf16 v[166:169], v[166:169], v[76:79], v[170:173]
	s_nop 5
	ds_read_b128 v[170:173], v156 offset:8640
	v_mfma_f32_16x16x32_bf16 v[166:169], v[174:177], v[64:67], v[166:169]
	ds_read_b128 v[174:177], v156 offset:8704
	s_waitcnt lgkmcnt(1)
	v_mfma_f32_16x16x32_bf16 v[166:169], v[170:173], v[68:71], v[166:169]
	ds_read_b128 v[170:173], v156 offset:8768
	s_waitcnt lgkmcnt(1)
	v_mfma_f32_16x16x32_bf16 v[166:169], v[174:177], v[80:83], v[166:169]
	ds_read_b128 v[174:177], v156 offset:8832
	s_waitcnt lgkmcnt(1)
	v_mfma_f32_16x16x32_bf16 v[166:169], v[170:173], v[84:87], v[166:169]
	ds_read_b128 v[170:173], v156 offset:8896
	s_waitcnt lgkmcnt(1)
	v_mfma_f32_16x16x32_bf16 v[166:169], v[174:177], v[88:91], v[166:169]
	s_waitcnt lgkmcnt(0)
	v_mfma_f32_16x16x32_bf16 v[170:173], v[170:173], v[92:95], v[166:169]
	s_nop 5
	v_mul_f32_e32 v169, 0x3db8aa3b, v162
	v_mul_f32_e32 v168, 0x3db8aa3b, v163
	v_max3_f32 v155, v169, s21, v168
	v_mul_f32_e32 v167, 0x3db8aa3b, v164
	v_mul_f32_e32 v166, 0x3db8aa3b, v165
	v_max3_f32 v155, v155, v167, v166
	v_mul_f32_e32 v165, 0x3db8aa3b, v170
	v_mul_f32_e32 v163, 0x3db8aa3b, v171
	v_max3_f32 v155, v155, v165, v163
	v_mul_f32_e32 v164, 0x3db8aa3b, v172
	v_mul_f32_e32 v162, 0x3db8aa3b, v173
	v_max3_f32 v170, v155, v164, v162
	ds_bpermute_b32 v171, v154, v170
	v_cndmask_b32_e32 v155, v148, v151, vcc
	v_lshlrev_b32_e32 v155, 2, v155
	s_waitcnt lgkmcnt(0)
	v_max_f32_e32 v171, v171, v171
	v_max_f32_e32 v170, v170, v171
	ds_bpermute_b32 v171, v155, v170
	s_waitcnt lgkmcnt(0)
	v_max3_f32 v170, v161, v170, v171
	v_cmp_gt_f32_e32 vcc, v170, v161
	s_cbranch_vccz .LBB0_616
	v_sub_f32_e32 v161, v161, v170
	v_exp_f32_e32 v172, v161
	v_mov_b32_e32 v161, v170
	v_pk_mul_f32 v[62:63], v[62:63], v[172:173] op_sel_hi:[1,0]
	v_pk_mul_f32 v[60:61], v[60:61], v[172:173] op_sel_hi:[1,0]
	v_pk_mul_f32 v[58:59], v[58:59], v[172:173] op_sel_hi:[1,0]
	v_pk_mul_f32 v[56:57], v[56:57], v[172:173] op_sel_hi:[1,0]
	v_pk_mul_f32 v[54:55], v[54:55], v[172:173] op_sel_hi:[1,0]
	v_pk_mul_f32 v[52:53], v[52:53], v[172:173] op_sel_hi:[1,0]
	v_pk_mul_f32 v[50:51], v[50:51], v[172:173] op_sel_hi:[1,0]
	v_pk_mul_f32 v[48:49], v[48:49], v[172:173] op_sel_hi:[1,0]
	v_pk_mul_f32 v[46:47], v[46:47], v[172:173] op_sel_hi:[1,0]
	v_pk_mul_f32 v[44:45], v[44:45], v[172:173] op_sel_hi:[1,0]
	v_pk_mul_f32 v[42:43], v[42:43], v[172:173] op_sel_hi:[1,0]
	v_pk_mul_f32 v[40:41], v[40:41], v[172:173] op_sel_hi:[1,0]
	v_pk_mul_f32 v[38:39], v[38:39], v[172:173] op_sel_hi:[1,0]
	v_pk_mul_f32 v[36:37], v[36:37], v[172:173] op_sel_hi:[1,0]
	v_pk_mul_f32 v[34:35], v[34:35], v[172:173] op_sel_hi:[1,0]
	v_pk_mul_f32 v[32:33], v[32:33], v[172:173] op_sel_hi:[1,0]
	v_pk_mul_f32 v[30:31], v[30:31], v[172:173] op_sel_hi:[1,0]
	v_pk_mul_f32 v[28:29], v[28:29], v[172:173] op_sel_hi:[1,0]
	v_pk_mul_f32 v[26:27], v[26:27], v[172:173] op_sel_hi:[1,0]
	v_pk_mul_f32 v[24:25], v[24:25], v[172:173] op_sel_hi:[1,0]
	v_pk_mul_f32 v[22:23], v[22:23], v[172:173] op_sel_hi:[1,0]
	v_pk_mul_f32 v[20:21], v[20:21], v[172:173] op_sel_hi:[1,0]
	v_pk_mul_f32 v[18:19], v[18:19], v[172:173] op_sel_hi:[1,0]
	v_pk_mul_f32 v[16:17], v[16:17], v[172:173] op_sel_hi:[1,0]
	v_pk_mul_f32 v[14:15], v[14:15], v[172:173] op_sel_hi:[1,0]
	v_pk_mul_f32 v[12:13], v[12:13], v[172:173] op_sel_hi:[1,0]
	v_pk_mul_f32 v[10:11], v[10:11], v[172:173] op_sel_hi:[1,0]
	v_pk_mul_f32 v[8:9], v[8:9], v[172:173] op_sel_hi:[1,0]
	v_pk_mul_f32 v[6:7], v[6:7], v[172:173] op_sel_hi:[1,0]
	v_pk_mul_f32 v[4:5], v[4:5], v[172:173] op_sel_hi:[1,0]
	v_pk_mul_f32 v[2:3], v[2:3], v[172:173] op_sel_hi:[1,0]
	v_pk_mul_f32 v[0:1], v[0:1], v[172:173] op_sel_hi:[1,0]
	v_mul_f32_e32 v128, v128, v172
	s_branch .LBB0_616
